# gate GEMM: 4x fp8 16x16x32 MFMA -> 1x f8f6f4 16x16x128 (fp8 e4m3 both operands)
# speedup vs baseline: 1.0296x; 1.0296x over previous
; #define G_STAGE(bufoff, gbase, o0, h64) do { \
;         __builtin_amdgcn_global_load_lds((const unsigned*)((const char*)(gbase) + (o0)), (LAS unsigned*)(lds + (bufoff) + ldsw), 16, 0, 0); \
;         __builtin_amdgcn_global_load_lds((const unsigned*)((const char*)(gbase) + (h64) + (o0)), (LAS unsigned*)(lds + (bufoff) + ldsw + 8192), 16, 0, 0); } while (0)
; #define G_WAIT_V(n) asm volatile("s_waitcnt vmcnt(" #n ")" ::: "memory")
; #define G_BAR __builtin_amdgcn_s_barrier()
;     ...
;     const int wid = __builtin_amdgcn_readfirstlane(tid >> 6), lane = tid & 63, wr = wid >> 2, wc = wid & 3, fr = lane & 15, fq = lane >> 4;
;     int R0, C0; stage_rc(tid * 16, R0, C0);
;     const unsigned Rb0 = (unsigned)((R0 & ~31) + perm32(R0 & 31)), c1 = (unsigned)(C0 >> 4), c0b = (unsigned)((C0 & 15) * 2);
;     const unsigned ldsw = (unsigned)wid * 1024u;
;     const int aoff = lds_byte(wr * 64 + fr, fq * 8), boff = lds_byte(wc * 32 + fr, fq * 8);
;     constexpr Shape cs = shape_of<PH, SUB>(); constexpr bool FP8 = (PH == PH_MERGE && (SUB & 1) == 0);
;     const unsigned cA0 = (unsigned)R0 * cs.rsA + c1 * cs.ssA + c0b, cB0 = (Rb0 * cs.Kb + (unsigned)C0) * 2u;
;     constexpr size_t chA = (size_t)128 * cs.rsA, ckA = (size_t)4 * cs.ssA, chB = (size_t)256 * cs.Kb, qA = (size_t)64 * cs.rsA, qB = (size_t)128 * cs.Kb, kB = 128;
;     constexpr int nt = cs.nt;
;     ...
;     Unit cur, nxt; int ui = 0;
;     if (!sched_next<PH, SUB>(E.ws, E.layer, 0, cur, E.x)) return;
;     f32x4 acc[2][2][4][2];
; #pragma unroll
;     for (int a = 0; a < 2; ++a)
; #pragma unroll
;         for (int b = 0; b < 2; ++b)
; #pragma unroll
;             for (int m = 0; m < 4; ++m)
; #pragma unroll
;                 for (int n = 0; n < 2; ++n) acc[a][b][m][n] = (f32x4){0.f, 0.f, 0.f, 0.f};
;     bf16x8 At[4][2], B0[2][2], B1[2][2];
;     const char* cA = cur.A; const char* cB = cur.B;
;     G_STAGE(G_SB(0, 0), cB, cB0, qB); G_STAGE(G_SA(0, 0), cA, cA0, qA); G_STAGE(G_SB(0, 1), cB + chB, cB0, qB); G_STAGE(G_SA(0, 1), cA + chA, cA0, qA);
;     if (wr == 1) G_BAR;
;     G_WAIT_V(4); G_BAR;
;     G_STAGE(G_SB(1, 0), cB + kB, cB0, qB); G_STAGE(G_SA(1, 0), cA + ckA, cA0, qA); G_STAGE(G_SB(1, 1), cB + chB + kB, cB0, qB);
;     G_WAIT_V(6); G_BAR;
.LBB0_866:
	v_and_b32_e32 v16, 15, v158
	v_and_b32_e32 v17, 48, v158
	v_lshlrev_b32_e32 v16, 6, v16
	v_lshlrev_b32_e32 v19, 2, v158
	v_or_b32_e32 v18, v16, v17
	s_lshl_b32 s4, s7, 13
	v_and_b32_e32 v19, 32, v19
	v_bitop3_b32 v18, v18, s4, v19 bitop3:0xde
	s_lshl_b32 s4, s6, 12
	v_bitop3_b32 v16, v16, v19, v17 bitop3:0x36
	s_and_b32 s4, s4, 0x3000
	v_or_b32_e32 v159, s4, v16
	v_lshl_add_u64 v[16:17], v[10:11], 0, s[46:47]
	s_add_i32 m0, s22, 0x18000
	s_mov_b64 s[4:5], 0x10080
	s_waitcnt vmcnt(4)
	s_barrier
	global_load_lds_dwordx4 v[16:17], off
	v_lshl_add_u64 v[16:17], v[10:11], 0, s[4:5]
	s_add_i32 m0, s22, 0x1a000
	s_add_i32 s26, s22, 0x8000
	global_load_lds_dwordx4 v[16:17], off
	v_lshl_add_u64 v[16:17], v[12:13], 0, s[46:47]
	s_mov_b32 m0, s26
	s_add_i32 s27, s22, 0xa000
	global_load_lds_dwordx4 v[16:17], off
	v_lshl_add_u64 v[12:13], v[12:13], 0, s[66:67]
	s_mov_b32 m0, s27
	s_mov_b64 s[4:5], 0x20080
	global_load_lds_dwordx4 v[12:13], off
	v_lshl_add_u64 v[12:13], v[10:11], 0, s[4:5]
	s_add_i32 m0, s22, 0x1c000
	s_mov_b64 s[4:5], 0x30080
	global_load_lds_dwordx4 v[12:13], off
	v_lshl_add_u64 v[10:11], v[10:11], 0, s[4:5]
	s_add_i32 m0, s22, 0x1e000
	s_mov_b32 s4, 0x16000
	global_load_lds_dwordx4 v[10:11], off
	s_waitcnt vmcnt(6)
	v_lshrrev_b32_e32 v11, 1, v14
	v_mul_lo_u32 v10, v9, s76
	s_add_u32 s29, s8, 0x2000000
	v_mad_u64_u32 v[10:11], s[4:5], v11, s4, v[10:11]
	s_addc_u32 s30, s9, 0
	v_add3_u32 v152, v10, v8, v15
	v_mov_b32_e32 v153, v1
	s_mov_b32 s33, 0
	v_add_u32_e32 v236, 0, v18
	s_mov_b32 s36, 0
	s_mov_b32 s31, 0
	s_barrier

; #define G_STAGE(bufoff, gbase, o0, h64) do { \
;         __builtin_amdgcn_global_load_lds((const unsigned*)((const char*)(gbase) + (o0)), (LAS unsigned*)(lds + (bufoff) + ldsw), 16, 0, 0); \
;         __builtin_amdgcn_global_load_lds((const unsigned*)((const char*)(gbase) + (h64) + (o0)), (LAS unsigned*)(lds + (bufoff) + ldsw + 8192), 16, 0, 0); } while (0)
; #define G_LDA(dst, b, h) do { _Pragma("unroll") for (int m = 0; m < 4; ++m) _Pragma("unroll") for (int k = 0; k < 2; ++k) dst[m][k] = *(const LAS bf16x8*)(lds + G_SA(b, h) + aoff + m * 2048 + k * 1024); } while (0)
; #define G_LDB(dst, b, h) do { _Pragma("unroll") for (int n = 0; n < 2; ++n) _Pragma("unroll") for (int k = 0; k < 2; ++k) dst[n][k] = *(const LAS bf16x8*)(lds + G_SB(b, h) + boff + n * 2048 + k * 1024); } while (0)
; #define G_WAIT_V(n) asm volatile("s_waitcnt vmcnt(" #n ")" ::: "memory")
; #define G_WAIT_L(n) asm volatile("s_waitcnt lgkmcnt(" #n ")" ::: "memory")
; #define G_BAR __builtin_amdgcn_s_barrier()
; #define G_SCHED __builtin_amdgcn_sched_barrier(0)
;     ...
;         for (int t = 0; t < nt; t += 2) {
;             const bool last = (t == nt - 2);
;             const char* a1 = cA + (size_t)(t + 1) * ckA;
;             const char* a2 = last ? nA : cA + (size_t)(t + 2) * ckA; const char* b2 = last ? nB : cB + (size_t)(t + 2) * kB;
;             const char* a3 = a2 + ckA; const char* b3 = b2 + kB;
;             G_LDB(B0, 0, 0); G_SCHED; G_LDA(At, 0, 0); G_STAGE(G_SA(1, 1), a1 + chA, cA0, qA);
;             G_WAIT_L(8); G_BAR; G_WAIT_L(0); G_MMA(0, 0, At, B0); G_BAR; G_SCHED;
;             G_LDB(B1, 0, 1); G_STAGE(G_SB(0, 0), b2, cB0, qB);
;             G_BAR; G_WAIT_L(0); G_MMA(0, 1, At, B1); G_BAR;
;             G_LDA(At, 0, 1); G_STAGE(G_SA(0, 0), a2, cA0, qA);
;             G_BAR; G_WAIT_L(0); G_MMA(1, 0, At, B0); G_BAR; G_SCHED;
;             G_STAGE(G_SB(0, 1), b2 + chB, cB0, qB);
;             G_WAIT_V(6); G_BAR; G_MMA(1, 1, At, B1); G_BAR;
;             G_LDB(B0, 1, 0); G_SCHED; G_LDA(At, 1, 0); G_STAGE(G_SA(0, 1), a2 + chA, cA0, qA);
;             G_WAIT_L(8); G_BAR; G_WAIT_L(0); G_MMA(0, 0, At, B0); G_BAR; G_SCHED;
.LBB0_872:
	s_add_u32 s4, s2, 0xfff50080
	s_addc_u32 s5, s3, -1
	s_add_i32 s40, 0, 0x10000
	v_add_u32_e32 v140, s40, v159
	ds_read_b128 v[144:147], v140
	ds_read_b128 v[148:151], v140 offset:1024
	ds_read_b128 v[136:139], v140 offset:2048
	ds_read_b128 v[140:143], v140 offset:3072
	s_cmp_eq_u32 s39, 4
	s_cselect_b32 s13, s9, s5
	s_cselect_b32 s12, s8, s4
	s_cselect_b32 s15, s11, s38
	s_cselect_b32 s14, s10, s37
	v_lshl_add_u64 v[154:155], s[2:3], 0, v[152:153]
	s_add_i32 m0, s22, 0xc000
	ds_read_b128 v[160:163], v236
	ds_read_b128 v[164:167], v236 offset:1024
	ds_read_b128 v[176:179], v236 offset:2048
	ds_read_b128 v[180:183], v236 offset:3072
	ds_read_b128 v[196:199], v236 offset:4096
	ds_read_b128 v[200:203], v236 offset:5120
	ds_read_b128 v[204:207], v236 offset:6144
	ds_read_b128 v[208:211], v236 offset:7168
	global_load_lds_dwordx4 v[154:155], off
	v_lshl_add_u64 v[154:155], v[154:155], 0, s[86:87]
	s_add_i32 m0, s22, 0xe000
	s_nop 0
	global_load_lds_dwordx4 v[154:155], off
	s_waitcnt lgkmcnt(8)
	s_barrier
	s_waitcnt lgkmcnt(0)
	s_setprio 3
	s_waitcnt lgkmcnt(0)
	v_mfma_f32_16x16x128_f8f6f4 v[128:131], v[144:151], v[160:167], v[128:131]
	v_mfma_f32_16x16x128_f8f6f4 v[132:135], v[136:143], v[160:167], v[132:135]
	v_mfma_f32_16x16x128_f8f6f4 v[112:115], v[144:151], v[176:183], v[112:115]
	v_mfma_f32_16x16x128_f8f6f4 v[116:119], v[136:143], v[176:183], v[116:119]
	v_mfma_f32_16x16x128_f8f6f4 v[96:99], v[144:151], v[196:203], v[96:99]
	v_mfma_f32_16x16x128_f8f6f4 v[100:103], v[136:143], v[196:203], v[100:103]
	v_mfma_f32_16x16x128_f8f6f4 v[80:83], v[144:151], v[204:211], v[80:83]
	v_mfma_f32_16x16x128_f8f6f4 v[84:87], v[136:143], v[204:211], v[84:87]
	s_setprio 0
	s_barrier
	s_add_i32 s4, 0, 0x14000
	v_add_u32_e32 v154, s4, v159
	s_add_i32 s5, s40, s17
	ds_read_b128 v[212:215], v154
	ds_read_b128 v[216:219], v154 offset:1024
	ds_read_b128 v[220:223], v154 offset:2048
	ds_read_b128 v[224:227], v154 offset:3072
	v_lshl_add_u64 v[154:155], s[14:15], 0, v[0:1]
	s_mov_b32 m0, s5
	v_lshl_add_u64 v[156:157], v[154:155], 0, s[50:51]
	global_load_lds_dwordx4 v[154:155], off
	s_add_i32 m0, s5, 0x2000
	s_nop 0
	global_load_lds_dwordx4 v[156:157], off
	s_barrier
	s_waitcnt lgkmcnt(0)
	s_setprio 3
	s_waitcnt lgkmcnt(0)
	v_mfma_f32_16x16x128_f8f6f4 v[124:127], v[212:219], v[160:167], v[124:127]
	v_mfma_f32_16x16x128_f8f6f4 v[120:123], v[220:227], v[160:167], v[120:123]
	v_mfma_f32_16x16x128_f8f6f4 v[108:111], v[212:219], v[176:183], v[108:111]
	v_mfma_f32_16x16x128_f8f6f4 v[104:107], v[220:227], v[176:183], v[104:107]
	v_mfma_f32_16x16x128_f8f6f4 v[92:95], v[212:219], v[196:203], v[92:95]
	v_mfma_f32_16x16x128_f8f6f4 v[88:91], v[220:227], v[196:203], v[88:91]
	v_mfma_f32_16x16x128_f8f6f4 v[76:79], v[212:219], v[204:211], v[76:79]
	v_mfma_f32_16x16x128_f8f6f4 v[72:75], v[220:227], v[204:211], v[72:75]
	s_setprio 0
	s_mov_b32 m0, s22
	v_lshl_add_u64 v[156:157], s[12:13], 0, v[2:3]
	s_barrier
	ds_read_b128 v[160:163], v236 offset:16384
	ds_read_b128 v[164:167], v236 offset:17408
	ds_read_b128 v[176:179], v236 offset:18432
	ds_read_b128 v[180:183], v236 offset:19456
	ds_read_b128 v[196:199], v236 offset:20480
	ds_read_b128 v[200:203], v236 offset:21504
	ds_read_b128 v[204:207], v236 offset:22528
	ds_read_b128 v[208:211], v236 offset:23552
	global_load_lds_dwordx4 v[156:157], off
	v_lshl_add_u64 v[234:235], v[156:157], 0, s[86:87]
	s_mov_b32 m0, s23
	s_nop 0
	global_load_lds_dwordx4 v[234:235], off
	s_barrier
	s_waitcnt lgkmcnt(0)
	s_setprio 3
	s_waitcnt lgkmcnt(0)
	v_mfma_f32_16x16x128_f8f6f4 v[64:67], v[144:151], v[160:167], v[64:67]
	v_mfma_f32_16x16x128_f8f6f4 v[68:71], v[136:143], v[160:167], v[68:71]
	v_mfma_f32_16x16x128_f8f6f4 v[48:51], v[144:151], v[176:183], v[48:51]
	v_mfma_f32_16x16x128_f8f6f4 v[52:55], v[136:143], v[176:183], v[52:55]
	v_mfma_f32_16x16x128_f8f6f4 v[32:35], v[144:151], v[196:203], v[32:35]
	v_mfma_f32_16x16x128_f8f6f4 v[36:39], v[136:143], v[196:203], v[36:39]
	v_mfma_f32_16x16x128_f8f6f4 v[20:23], v[144:151], v[204:211], v[20:23]
	v_mfma_f32_16x16x128_f8f6f4 v[16:19], v[136:143], v[204:211], v[16:19]
	s_setprio 0
	s_barrier
	s_add_i32 s4, s4, s17
	v_lshl_add_u64 v[140:141], v[154:155], 0, s[0:1]
	s_mov_b32 m0, s4
	s_nop 0
	global_load_lds_dwordx4 v[140:141], off
	v_lshl_add_u64 v[140:141], v[154:155], 0, s[52:53]
	s_add_i32 m0, s4, 0x2000
	s_nop 0
	global_load_lds_dwordx4 v[140:141], off
	s_waitcnt vmcnt(6)
	s_barrier
	s_setprio 3
	v_mfma_f32_16x16x128_f8f6f4 v[60:63], v[212:219], v[160:167], v[60:63]
	v_mfma_f32_16x16x128_f8f6f4 v[56:59], v[220:227], v[160:167], v[56:59]
	v_mfma_f32_16x16x128_f8f6f4 v[44:47], v[212:219], v[176:183], v[44:47]
	v_mfma_f32_16x16x128_f8f6f4 v[40:43], v[220:227], v[176:183], v[40:43]
	v_mfma_f32_16x16x128_f8f6f4 v[28:31], v[212:219], v[196:203], v[28:31]
	v_mfma_f32_16x16x128_f8f6f4 v[24:27], v[220:227], v[196:203], v[24:27]
	v_mfma_f32_16x16x128_f8f6f4 v[12:15], v[212:219], v[204:211], v[12:15]
	v_mfma_f32_16x16x128_f8f6f4 v[8:11], v[220:227], v[204:211], v[8:11]
	s_setprio 0
	s_add_i32 s4, 0, 0x18000
	v_add_u32_e32 v140, s4, v159
	s_barrier
	ds_read_b128 v[144:147], v140
	ds_read_b128 v[148:151], v140 offset:1024
	ds_read_b128 v[136:139], v140 offset:2048
	ds_read_b128 v[140:143], v140 offset:3072
	s_mov_b32 m0, s24
	v_lshl_add_u64 v[234:235], v[156:157], 0, s[88:89]
	ds_read_b128 v[160:163], v236 offset:32768
	ds_read_b128 v[164:167], v236 offset:33792
	ds_read_b128 v[176:179], v236 offset:34816
	ds_read_b128 v[180:183], v236 offset:35840
	ds_read_b128 v[196:199], v236 offset:36864
	ds_read_b128 v[200:203], v236 offset:37888
	ds_read_b128 v[204:207], v236 offset:38912
	ds_read_b128 v[208:211], v236 offset:39936
	global_load_lds_dwordx4 v[234:235], off
	v_lshl_add_u64 v[234:235], v[156:157], 0, s[64:65]
	s_mov_b32 m0, s25
	s_nop 0
	global_load_lds_dwordx4 v[234:235], off
	s_waitcnt lgkmcnt(8)
	s_barrier
; #define G_STAGE(bufoff, gbase, o0, h64) do { \
;         __builtin_amdgcn_global_load_lds((const unsigned*)((const char*)(gbase) + (o0)), (LAS unsigned*)(lds + (bufoff) + ldsw), 16, 0, 0); \
;         __builtin_amdgcn_global_load_lds((const unsigned*)((const char*)(gbase) + (h64) + (o0)), (LAS unsigned*)(lds + (bufoff) + ldsw + 8192), 16, 0, 0); } while (0)
; #define G_LDA(dst, b, h) do { _Pragma("unroll") for (int m = 0; m < 4; ++m) _Pragma("unroll") for (int k = 0; k < 2; ++k) dst[m][k] = *(const LAS bf16x8*)(lds + G_SA(b, h) + aoff + m * 2048 + k * 1024); } while (0)
; #define G_LDB(dst, b, h) do { _Pragma("unroll") for (int n = 0; n < 2; ++n) _Pragma("unroll") for (int k = 0; k < 2; ++k) dst[n][k] = *(const LAS bf16x8*)(lds + G_SB(b, h) + boff + n * 2048 + k * 1024); } while (0)
; #define G_WAIT_V(n) asm volatile("s_waitcnt vmcnt(" #n ")" ::: "memory")
; #define G_WAIT_L(n) asm volatile("s_waitcnt lgkmcnt(" #n ")" ::: "memory")
; #define G_BAR __builtin_amdgcn_s_barrier()
; #define G_SCHED __builtin_amdgcn_sched_barrier(0)
;     __device__ __forceinline__ void get_rs(const Unit& u, int wr, int fr, float (&rs)[8]) const {
; #pragma unroll
;         for (int r8 = 0; r8 < 8; ++r8) rs[r8] = rstab[u.ord * 256 + (r8 >> 2) * 128 + wr * 64 + (r8 & 3) * 16 + fr];
;     }
;     ...
;             G_WAIT_L(8); G_BAR; G_WAIT_L(0); G_MMA(0, 0, At, B0); G_BAR; G_SCHED;
;             G_LDB(B1, 1, 1); G_STAGE(G_SB(1, 0), b3, cB0, qB);
;             G_BAR; G_WAIT_L(0); G_MMA(0, 1, At, B1); G_BAR;
;             G_LDA(At, 1, 1); G_STAGE(G_SA(1, 0), a3, cA0, qA);
;             G_BAR; G_WAIT_L(0); G_MMA(1, 0, At, B0); G_BAR; G_SCHED;
;             G_STAGE(G_SB(1, 1), b3 + chB, cB0, qB);
;             G_WAIT_V(6); G_BAR; G_MMA(1, 1, At, B1); G_BAR;
;         }
;         E.template run<cs.kind>(acc, cur, tid);
	s_waitcnt lgkmcnt(0)
	s_setprio 3
	s_waitcnt lgkmcnt(0)
	v_mfma_f32_16x16x128_f8f6f4 v[128:131], v[144:151], v[160:167], v[128:131]
	v_mfma_f32_16x16x128_f8f6f4 v[132:135], v[136:143], v[160:167], v[132:135]
	v_mfma_f32_16x16x128_f8f6f4 v[112:115], v[144:151], v[176:183], v[112:115]
	v_mfma_f32_16x16x128_f8f6f4 v[116:119], v[136:143], v[176:183], v[116:119]
	v_mfma_f32_16x16x128_f8f6f4 v[96:99], v[144:151], v[196:203], v[96:99]
	v_mfma_f32_16x16x128_f8f6f4 v[100:103], v[136:143], v[196:203], v[100:103]
	v_mfma_f32_16x16x128_f8f6f4 v[80:83], v[144:151], v[204:211], v[80:83]
	v_mfma_f32_16x16x128_f8f6f4 v[84:87], v[136:143], v[204:211], v[84:87]
	s_setprio 0
	s_barrier
	s_add_i32 s5, 0, 0x1c000
	s_add_i32 s4, s4, s17
	v_add_u32_e32 v237, s5, v159
	v_lshl_add_u64 v[234:235], v[154:155], 0, s[46:47]
	s_mov_b32 m0, s4
	ds_read_b128 v[212:215], v237
	ds_read_b128 v[216:219], v237 offset:1024
	ds_read_b128 v[220:223], v237 offset:2048
	ds_read_b128 v[224:227], v237 offset:3072
	global_load_lds_dwordx4 v[234:235], off
	v_lshl_add_u64 v[234:235], v[154:155], 0, s[54:55]
	s_add_i32 m0, s4, 0x2000
	s_nop 0
	global_load_lds_dwordx4 v[234:235], off
	s_barrier
	s_waitcnt lgkmcnt(0)
	s_setprio 3
	s_waitcnt lgkmcnt(0)
	v_mfma_f32_16x16x128_f8f6f4 v[124:127], v[212:219], v[160:167], v[124:127]
	v_mfma_f32_16x16x128_f8f6f4 v[120:123], v[220:227], v[160:167], v[120:123]
	v_mfma_f32_16x16x128_f8f6f4 v[108:111], v[212:219], v[176:183], v[108:111]
	v_mfma_f32_16x16x128_f8f6f4 v[104:107], v[220:227], v[176:183], v[104:107]
	v_mfma_f32_16x16x128_f8f6f4 v[92:95], v[212:219], v[196:203], v[92:95]
	v_mfma_f32_16x16x128_f8f6f4 v[88:91], v[220:227], v[196:203], v[88:91]
	v_mfma_f32_16x16x128_f8f6f4 v[76:79], v[212:219], v[204:211], v[76:79]
	v_mfma_f32_16x16x128_f8f6f4 v[72:75], v[220:227], v[204:211], v[72:75]
	s_setprio 0
	s_mov_b32 m0, s26
	v_lshl_add_u64 v[234:235], v[156:157], 0, s[46:47]
	s_barrier
	ds_read_b128 v[160:163], v236 offset:49152
	ds_read_b128 v[164:167], v236 offset:50176
	ds_read_b128 v[176:179], v236 offset:51200
	ds_read_b128 v[180:183], v236 offset:52224
	ds_read_b128 v[196:199], v236 offset:53248
	ds_read_b128 v[200:203], v236 offset:54272
	ds_read_b128 v[204:207], v236 offset:55296
	ds_read_b128 v[208:211], v236 offset:56320
	global_load_lds_dwordx4 v[234:235], off
	v_lshl_add_u64 v[156:157], v[156:157], 0, s[66:67]
	s_mov_b32 m0, s27
	s_nop 0
	global_load_lds_dwordx4 v[156:157], off
	s_barrier
	s_waitcnt lgkmcnt(0)
	s_setprio 3
	s_waitcnt lgkmcnt(0)
	v_mfma_f32_16x16x128_f8f6f4 v[64:67], v[144:151], v[160:167], v[64:67]
	v_mfma_f32_16x16x128_f8f6f4 v[68:71], v[136:143], v[160:167], v[68:71]
	v_mfma_f32_16x16x128_f8f6f4 v[48:51], v[144:151], v[176:183], v[48:51]
	v_mfma_f32_16x16x128_f8f6f4 v[52:55], v[136:143], v[176:183], v[52:55]
	v_mfma_f32_16x16x128_f8f6f4 v[32:35], v[144:151], v[196:203], v[32:35]
	v_mfma_f32_16x16x128_f8f6f4 v[36:39], v[136:143], v[196:203], v[36:39]
	v_mfma_f32_16x16x128_f8f6f4 v[20:23], v[144:151], v[204:211], v[20:23]
	v_mfma_f32_16x16x128_f8f6f4 v[16:19], v[136:143], v[204:211], v[16:19]
	s_setprio 0
	s_barrier
	s_add_i32 s4, s5, s17
	v_lshl_add_u64 v[140:141], v[154:155], 0, s[42:43]
	s_mov_b32 m0, s4
	s_nop 0
	global_load_lds_dwordx4 v[140:141], off
	v_lshl_add_u64 v[140:141], v[154:155], 0, s[58:59]
	s_add_i32 m0, s4, 0x2000
	s_nop 0
	global_load_lds_dwordx4 v[140:141], off
	s_waitcnt vmcnt(6)
	s_barrier
	s_setprio 3
	v_mfma_f32_16x16x128_f8f6f4 v[60:63], v[212:219], v[160:167], v[60:63]
	v_mfma_f32_16x16x128_f8f6f4 v[56:59], v[220:227], v[160:167], v[56:59]
	v_mfma_f32_16x16x128_f8f6f4 v[44:47], v[212:219], v[176:183], v[44:47]
	v_mfma_f32_16x16x128_f8f6f4 v[40:43], v[220:227], v[176:183], v[40:43]
	v_mfma_f32_16x16x128_f8f6f4 v[28:31], v[212:219], v[196:203], v[28:31]
	v_mfma_f32_16x16x128_f8f6f4 v[24:27], v[220:227], v[196:203], v[24:27]
	v_mfma_f32_16x16x128_f8f6f4 v[12:15], v[212:219], v[204:211], v[12:15]
	v_mfma_f32_16x16x128_f8f6f4 v[8:11], v[220:227], v[204:211], v[8:11]
	s_setprio 0
	s_add_i32 s39, s39, 2
	s_add_u32 s2, s2, 0x100
	s_addc_u32 s3, s3, 0
	s_add_u32 s37, s37, 0x100
	s_addc_u32 s38, s38, 0
	s_cmp_gt_u32 s39, 5
	s_barrier
	s_cbranch_scc0 .LBB0_872
	v_mov_b32_e32 v142, v158
	s_lshl_b32 s3, s33, 10
	v_readfirstlane_b32 s2, v142
	s_add_i32 s3, s3, 0
	s_and_b32 s2, s2, 0xffffff00
	v_and_b32_e32 v136, 15, v142
	s_add_i32 s3, s3, s2
	v_lshl_add_u32 v136, v136, 2, s3
	v_add_u32_e32 v136, 0x20010, v136
	ds_read2_b32 v[144:145], v136 offset1:16
	ds_read2_b32 v[140:141], v136 offset0:32 offset1:48
	ds_read2_b32 v[138:139], v136 offset0:128 offset1:144
	ds_read2_b32 v[136:137], v136 offset0:160 offset1:176
	s_and_b32 s2, s33, 1
	s_waitcnt lgkmcnt(0)
; __device__ __forceinline__ unsigned cvt_pk_bf16(float lo, float hi) { unsigned r; asm volatile("v_cvt_pk_bf16_f32 %0, %1, %2" : "=v"(r) : "v"(lo), "v"(hi)); return r; }
; __device__ __forceinline__ float bf_lo(unsigned w) { return __uint_as_float(w << 16); }
; __device__ __forceinline__ float bf_hi(unsigned w) { return __uint_as_float(w & 0xffff0000u); }
; #define MEMFENCE asm volatile("" ::: "memory")
; __device__ __forceinline__ float sigmoidf_(float v) { return __builtin_amdgcn_rcpf(1.0f + __expf(-v)); }
; __device__ __forceinline__ u32x4 pack8(const f32x4 a, const f32x4 b) { u32x4 w; w.x = cvt_pk_bf16(a[0], a[1]); w.y = cvt_pk_bf16(a[2], a[3]); w.z = cvt_pk_bf16(b[0], b[1]); w.w = cvt_pk_bf16(b[2], b[3]); return w; }
; __device__ __forceinline__ void unpack8(const u32x4 w, f32x4& a, f32x4& b) { a[0] = bf_lo(w.x); a[1] = bf_hi(w.x); a[2] = bf_lo(w.y); a[3] = bf_hi(w.y); b[0] = bf_lo(w.z); b[1] = bf_hi(w.z); b[2] = bf_lo(w.w); b[3] = bf_hi(w.w); }
; __device__ __forceinline__ unsigned pack4_u8c(const f32x4 v) { const unsigned q0 = (unsigned)fmaxf(v[0] * 255.0f + 0.5f, 1.0f), q1 = (unsigned)fmaxf(v[1] * 255.0f + 0.5f, 1.0f), q2 = (unsigned)fmaxf(v[2] * 255.0f + 0.5f, 1.0f), q3 = (unsigned)fmaxf(v[3] * 255.0f + 0.5f, 1.0f);
;     template <int KIND> __device__ __forceinline__ void run(f32x4 (&acc)[2][2][4][2], const Unit& u, int tid_in) const {
;     ...
;         if constexpr (KIND == K_MG_G) { float rs[8]; get_rs(u, wr, fr, rs);
;             u32x4* gst = (u32x4*)((unsigned char*)x + 32 * MiB) + ((size_t)(blockIdx.x * 2 + (u.ord & 1)) * 3 + u.aux) * 4096;
; #pragma unroll
;             for (int ai = 0; ai < 2; ++ai)
; #pragma unroll
;                 for (int m = 0; m < 4; ++m) { const float r = rs[ai * 4 + m] * (1.0f / GATE_WSCALE); u32x4 w;
; #pragma unroll
;                     for (int bj = 0; bj < 2; ++bj) { f32x4 a = acc[ai][bj][m][0] * r, b = acc[ai][bj][m][1] * r;
; #pragma unroll
;                         for (int j = 0; j < 4; ++j) { a[j] = sigmoidf_(a[j]); b[j] = sigmoidf_(b[j]); }
;                         if (bj == 0) { w.x = pack4_u8c(a); w.y = pack4_u8c(b); } else { w.z = pack4_u8c(a); w.w = pack4_u8c(b); } }
;                     gst[(ai * 4 + m) * 512 + tid] = w; MEMFENCE; }
	v_mul_f32_e32 v144, 0x3c800000, v144
	v_pk_mul_f32 v[128:129], v[128:129], v[144:145] op_sel_hi:[1,0]
	v_pk_mul_f32 v[130:131], v[130:131], v[144:145] op_sel_hi:[1,0]
	v_mul_f32_e32 v128, 0xbfb8aa3b, v128
	v_mul_f32_e32 v129, 0xbfb8aa3b, v129
	v_mul_f32_e32 v131, 0xbfb8aa3b, v131
	v_exp_f32_e32 v128, v128
	v_exp_f32_e32 v129, v129
	v_mul_f32_e32 v130, 0xbfb8aa3b, v130
	v_exp_f32_e32 v131, v131
	v_exp_f32_e32 v130, v130
	v_add_f32_e32 v128, 1.0, v128
	v_add_f32_e32 v129, 1.0, v129
	s_or_b32 s2, s2, s60
	v_pk_mul_f32 v[132:133], v[132:133], v[144:145] op_sel_hi:[1,0]
	v_add_f32_e32 v131, 1.0, v131
	v_rcp_f32_e32 v128, v128
	v_rcp_f32_e32 v129, v129
	v_add_f32_e32 v130, 1.0, v130
	s_mul_hi_u32 s3, s2, 3
	s_mul_i32 s2, s2, 3
	s_ashr_i32 s4, s36, 31
	v_pk_mul_f32 v[134:135], v[134:135], v[144:145] op_sel_hi:[1,0]
	v_mul_f32_e32 v132, 0xbfb8aa3b, v132
	v_mul_f32_e32 v133, 0xbfb8aa3b, v133
	v_rcp_f32_e32 v131, v131
	v_rcp_f32_e32 v130, v130
	s_add_u32 s2, s2, s36
	v_mul_f32_e32 v135, 0xbfb8aa3b, v135
	v_exp_f32_e32 v132, v132
	v_exp_f32_e32 v133, v133
	v_mul_f32_e32 v134, 0xbfb8aa3b, v134
	s_addc_u32 s3, s3, s4
	v_exp_f32_e32 v135, v135
	v_exp_f32_e32 v134, v134
	s_mov_b32 s4, 0x437f0000
	v_fma_f32 v128, v128, s4, 0.5
	v_fma_f32 v129, v129, s4, 0.5
	v_max_f32_e32 v128, 1.0, v128
	v_max_f32_e32 v129, 1.0, v129
	v_fma_f32 v130, v130, s4, 0.5
	v_fma_f32 v131, v131, s4, 0.5
	v_add_f32_e32 v132, 1.0, v132
	v_add_f32_e32 v133, 1.0, v133
	v_cvt_u32_f32_e32 v128, v128
	v_cvt_u32_f32_e32 v129, v129
	v_max_f32_e32 v130, 1.0, v130
	v_max_f32_e32 v131, 1.0, v131
	v_add_f32_e32 v135, 1.0, v135
	v_rcp_f32_e32 v132, v132
	v_rcp_f32_e32 v133, v133
	v_cvt_u32_f32_sdwa v130, v130 dst_sel:WORD_1 dst_unused:UNUSED_PAD src0_sel:DWORD
	v_cvt_u32_f32_sdwa v131, v131 dst_sel:BYTE_3 dst_unused:UNUSED_PAD src0_sel:DWORD
	v_add_f32_e32 v134, 1.0, v134
	v_rcp_f32_e32 v135, v135
	v_rcp_f32_e32 v134, v134
	v_lshl_or_b32 v128, v129, 8, v128
	v_or3_b32 v128, v128, v130, v131
	v_fma_f32 v129, v132, s4, 0.5
	v_fma_f32 v130, v133, s4, 0.5
	v_pk_mul_f32 v[124:125], v[124:125], v[144:145] op_sel_hi:[1,0]
	v_max_f32_e32 v129, 1.0, v129
	v_max_f32_e32 v130, 1.0, v130
	v_fma_f32 v131, v134, s4, 0.5
	v_fma_f32 v132, v135, s4, 0.5
	v_mul_f32_e32 v125, 0xbfb8aa3b, v125
	v_cvt_u32_f32_e32 v129, v129
	v_cvt_u32_f32_e32 v130, v130
	v_max_f32_e32 v131, 1.0, v131
	v_max_f32_e32 v132, 1.0, v132
	v_exp_f32_e32 v125, v125
	v_cvt_u32_f32_sdwa v131, v131 dst_sel:WORD_1 dst_unused:UNUSED_PAD src0_sel:DWORD
	v_cvt_u32_f32_sdwa v132, v132 dst_sel:BYTE_3 dst_unused:UNUSED_PAD src0_sel:DWORD
	v_pk_mul_f32 v[120:121], v[120:121], v[144:145] op_sel_hi:[1,0]
	v_mul_f32_e32 v124, 0xbfb8aa3b, v124
	v_mul_f32_e32 v121, 0xbfb8aa3b, v121
	v_lshl_or_b32 v129, v130, 8, v129
	v_exp_f32_e32 v130, v124
	v_add_f32_e32 v124, 1.0, v125
	v_exp_f32_e32 v121, v121
	v_or3_b32 v129, v129, v131, v132
	v_rcp_f32_e32 v131, v124
	v_mul_f32_e32 v120, 0xbfb8aa3b, v120
	v_pk_mul_f32 v[124:125], v[126:127], v[144:145] op_sel_hi:[1,0]
	v_add_f32_e32 v126, 1.0, v130
	v_exp_f32_e32 v130, v120
	v_add_f32_e32 v120, 1.0, v121
	v_fma_f32 v127, v131, s4, 0.5
	v_rcp_f32_e32 v131, v120
	v_pk_mul_f32 v[120:121], v[122:123], v[144:145] op_sel_hi:[1,0]
	v_add_f32_e32 v122, 1.0, v130
	v_mul_f32_e32 v120, 0xbfb8aa3b, v120
	v_mul_f32_e32 v121, 0xbfb8aa3b, v121
	v_exp_f32_e32 v120, v120
	v_exp_f32_e32 v121, v121
	v_rcp_f32_e32 v122, v122
	v_fma_f32 v123, v131, s4, 0.5
	v_add_f32_e32 v120, 1.0, v120
	v_add_f32_e32 v121, 1.0, v121
	v_rcp_f32_e32 v120, v120
	v_rcp_f32_e32 v121, v121
	v_fma_f32 v122, v122, s4, 0.5
	v_max_f32_e32 v123, 1.0, v123
	v_max_f32_e32 v122, 1.0, v122
	v_fma_f32 v120, v120, s4, 0.5
	v_fma_f32 v121, v121, s4, 0.5
	v_cvt_u32_f32_e32 v123, v123
	v_cvt_u32_f32_e32 v122, v122
	v_max_f32_e32 v120, 1.0, v120
	v_max_f32_e32 v121, 1.0, v121
	v_cvt_u32_f32_sdwa v120, v120 dst_sel:WORD_1 dst_unused:UNUSED_PAD src0_sel:DWORD
	v_cvt_u32_f32_sdwa v121, v121 dst_sel:BYTE_3 dst_unused:UNUSED_PAD src0_sel:DWORD
	v_lshl_or_b32 v122, v123, 8, v122
	v_mul_f32_e32 v124, 0xbfb8aa3b, v124
	v_mul_f32_e32 v125, 0xbfb8aa3b, v125
	v_or3_b32 v131, v122, v120, v121
	v_mul_f32_e32 v122, 0x3c800000, v145
	v_pk_mul_f32 v[112:113], v[112:113], v[122:123] op_sel_hi:[1,0]
	v_pk_mul_f32 v[114:115], v[114:115], v[122:123] op_sel_hi:[1,0]
	v_mul_f32_e32 v112, 0xbfb8aa3b, v112
	v_mul_f32_e32 v113, 0xbfb8aa3b, v113
	v_mul_f32_e32 v115, 0xbfb8aa3b, v115
	v_exp_f32_e32 v112, v112
	v_exp_f32_e32 v113, v113
	v_mul_f32_e32 v114, 0xbfb8aa3b, v114
	v_exp_f32_e32 v115, v115
	v_exp_f32_e32 v114, v114
	v_add_f32_e32 v112, 1.0, v112
	v_add_f32_e32 v113, 1.0, v113
	v_pk_mul_f32 v[116:117], v[116:117], v[122:123] op_sel_hi:[1,0]
	v_add_f32_e32 v115, 1.0, v115
	v_rcp_f32_e32 v112, v112
	v_rcp_f32_e32 v113, v113
	v_add_f32_e32 v114, 1.0, v114
	v_pk_mul_f32 v[118:119], v[118:119], v[122:123] op_sel_hi:[1,0]
	v_mul_f32_e32 v116, 0xbfb8aa3b, v116
	v_mul_f32_e32 v117, 0xbfb8aa3b, v117
	v_rcp_f32_e32 v115, v115
	v_rcp_f32_e32 v114, v114
	v_mul_f32_e32 v119, 0xbfb8aa3b, v119
	v_exp_f32_e32 v116, v116
	v_exp_f32_e32 v117, v117
	v_mul_f32_e32 v118, 0xbfb8aa3b, v118
	v_exp_f32_e32 v119, v119
	v_exp_f32_e32 v118, v118
	v_fma_f32 v112, v112, s4, 0.5
	v_fma_f32 v113, v113, s4, 0.5
	v_max_f32_e32 v112, 1.0, v112
	v_max_f32_e32 v113, 1.0, v113
	v_fma_f32 v114, v114, s4, 0.5
	v_fma_f32 v115, v115, s4, 0.5
	v_add_f32_e32 v116, 1.0, v116
	v_add_f32_e32 v117, 1.0, v117
	v_cvt_u32_f32_e32 v112, v112
	v_cvt_u32_f32_e32 v113, v113
	v_max_f32_e32 v114, 1.0, v114
	v_max_f32_e32 v115, 1.0, v115
	v_add_f32_e32 v119, 1.0, v119
	v_rcp_f32_e32 v116, v116
	v_rcp_f32_e32 v117, v117
; __device__ __forceinline__ unsigned cvt_pk_bf16(float lo, float hi) { unsigned r; asm volatile("v_cvt_pk_bf16_f32 %0, %1, %2" : "=v"(r) : "v"(lo), "v"(hi)); return r; }
; __device__ __forceinline__ float bf_lo(unsigned w) { return __uint_as_float(w << 16); }
; __device__ __forceinline__ float bf_hi(unsigned w) { return __uint_as_float(w & 0xffff0000u); }
; #define MEMFENCE asm volatile("" ::: "memory")
; __device__ __forceinline__ float sigmoidf_(float v) { return __builtin_amdgcn_rcpf(1.0f + __expf(-v)); }
; __device__ __forceinline__ u32x4 pack8(const f32x4 a, const f32x4 b) { u32x4 w; w.x = cvt_pk_bf16(a[0], a[1]); w.y = cvt_pk_bf16(a[2], a[3]); w.z = cvt_pk_bf16(b[0], b[1]); w.w = cvt_pk_bf16(b[2], b[3]); return w; }
; __device__ __forceinline__ void unpack8(const u32x4 w, f32x4& a, f32x4& b) { a[0] = bf_lo(w.x); a[1] = bf_hi(w.x); a[2] = bf_lo(w.y); a[3] = bf_hi(w.y); b[0] = bf_lo(w.z); b[1] = bf_hi(w.z); b[2] = bf_lo(w.w); b[3] = bf_hi(w.w); }
; __device__ __forceinline__ unsigned pack4_u8c(const f32x4 v) { const unsigned q0 = (unsigned)fmaxf(v[0] * 255.0f + 0.5f, 1.0f), q1 = (unsigned)fmaxf(v[1] * 255.0f + 0.5f, 1.0f), q2 = (unsigned)fmaxf(v[2] * 255.0f + 0.5f, 1.0f), q3 = (unsigned)fmaxf(v[3] * 255.0f + 0.5f, 1.0f);
;     template <int KIND> __device__ __forceinline__ void run(f32x4 (&acc)[2][2][4][2], const Unit& u, int tid_in) const {
;     ...
;                 for (int m = 0; m < 4; ++m) { const float r = rs[ai * 4 + m] * (1.0f / GATE_WSCALE); u32x4 w;
; #pragma unroll
;                     for (int bj = 0; bj < 2; ++bj) { f32x4 a = acc[ai][bj][m][0] * r, b = acc[ai][bj][m][1] * r;
; #pragma unroll
;                         for (int j = 0; j < 4; ++j) { a[j] = sigmoidf_(a[j]); b[j] = sigmoidf_(b[j]); }
;                         if (bj == 0) { w.x = pack4_u8c(a); w.y = pack4_u8c(b); } else { w.z = pack4_u8c(a); w.w = pack4_u8c(b); } }
;                     gst[(ai * 4 + m) * 512 + tid] = w; MEMFENCE; }
	v_cvt_u32_f32_sdwa v114, v114 dst_sel:WORD_1 dst_unused:UNUSED_PAD src0_sel:DWORD
	v_cvt_u32_f32_sdwa v115, v115 dst_sel:BYTE_3 dst_unused:UNUSED_PAD src0_sel:DWORD
	v_add_f32_e32 v118, 1.0, v118
	v_rcp_f32_e32 v119, v119
	v_rcp_f32_e32 v118, v118
	v_lshl_or_b32 v112, v113, 8, v112
	v_or3_b32 v112, v112, v114, v115
	v_fma_f32 v113, v116, s4, 0.5
	v_fma_f32 v114, v117, s4, 0.5
	v_pk_mul_f32 v[108:109], v[108:109], v[122:123] op_sel_hi:[1,0]
	v_max_f32_e32 v113, 1.0, v113
	v_max_f32_e32 v114, 1.0, v114
	v_fma_f32 v115, v118, s4, 0.5
	v_fma_f32 v116, v119, s4, 0.5
	v_mul_f32_e32 v109, 0xbfb8aa3b, v109
	v_cvt_u32_f32_e32 v113, v113
	v_cvt_u32_f32_e32 v114, v114
	v_max_f32_e32 v115, 1.0, v115
	v_max_f32_e32 v116, 1.0, v116
	v_exp_f32_e32 v109, v109
	v_cvt_u32_f32_sdwa v115, v115 dst_sel:WORD_1 dst_unused:UNUSED_PAD src0_sel:DWORD
	v_cvt_u32_f32_sdwa v116, v116 dst_sel:BYTE_3 dst_unused:UNUSED_PAD src0_sel:DWORD
	v_pk_mul_f32 v[104:105], v[104:105], v[122:123] op_sel_hi:[1,0]
	v_mul_f32_e32 v108, 0xbfb8aa3b, v108
	v_mul_f32_e32 v105, 0xbfb8aa3b, v105
	v_lshl_or_b32 v113, v114, 8, v113
	v_exp_f32_e32 v114, v108
	v_add_f32_e32 v108, 1.0, v109
	v_exp_f32_e32 v105, v105
	v_or3_b32 v113, v113, v115, v116
	v_rcp_f32_e32 v115, v108
	v_mul_f32_e32 v104, 0xbfb8aa3b, v104
	v_pk_mul_f32 v[108:109], v[110:111], v[122:123] op_sel_hi:[1,0]
	v_add_f32_e32 v110, 1.0, v114
	v_exp_f32_e32 v114, v104
	v_add_f32_e32 v104, 1.0, v105
	v_fma_f32 v111, v115, s4, 0.5
	v_rcp_f32_e32 v115, v104
	v_pk_mul_f32 v[104:105], v[106:107], v[122:123] op_sel_hi:[1,0]
	v_add_f32_e32 v106, 1.0, v114
	v_mul_f32_e32 v104, 0xbfb8aa3b, v104
	v_mul_f32_e32 v105, 0xbfb8aa3b, v105
	v_exp_f32_e32 v104, v104
	v_exp_f32_e32 v105, v105
	v_rcp_f32_e32 v106, v106
	v_fma_f32 v107, v115, s4, 0.5
	v_add_f32_e32 v104, 1.0, v104
	v_add_f32_e32 v105, 1.0, v105
	v_rcp_f32_e32 v104, v104
	v_rcp_f32_e32 v105, v105
	v_fma_f32 v106, v106, s4, 0.5
	v_max_f32_e32 v107, 1.0, v107
	v_max_f32_e32 v106, 1.0, v106
	v_fma_f32 v104, v104, s4, 0.5
	v_fma_f32 v105, v105, s4, 0.5
	v_cvt_u32_f32_e32 v107, v107
	v_cvt_u32_f32_e32 v106, v106
	v_max_f32_e32 v104, 1.0, v104
	v_max_f32_e32 v105, 1.0, v105
	v_cvt_u32_f32_sdwa v104, v104 dst_sel:WORD_1 dst_unused:UNUSED_PAD src0_sel:DWORD
	v_cvt_u32_f32_sdwa v105, v105 dst_sel:BYTE_3 dst_unused:UNUSED_PAD src0_sel:DWORD
	v_lshl_or_b32 v106, v107, 8, v106
	v_exp_f32_e32 v124, v124
	v_exp_f32_e32 v125, v125
	v_or3_b32 v115, v106, v104, v105
	v_mul_f32_e32 v106, 0x3c800000, v140
	v_pk_mul_f32 v[96:97], v[96:97], v[106:107] op_sel_hi:[1,0]
	v_pk_mul_f32 v[98:99], v[98:99], v[106:107] op_sel_hi:[1,0]
	v_mul_f32_e32 v96, 0xbfb8aa3b, v96
	v_mul_f32_e32 v97, 0xbfb8aa3b, v97
	v_mul_f32_e32 v99, 0xbfb8aa3b, v99
	v_exp_f32_e32 v96, v96
	v_exp_f32_e32 v97, v97
	v_mul_f32_e32 v98, 0xbfb8aa3b, v98
	v_exp_f32_e32 v99, v99
	v_exp_f32_e32 v98, v98
	v_add_f32_e32 v96, 1.0, v96
	v_add_f32_e32 v97, 1.0, v97
	v_pk_mul_f32 v[100:101], v[100:101], v[106:107] op_sel_hi:[1,0]
	v_add_f32_e32 v99, 1.0, v99
	v_rcp_f32_e32 v96, v96
	v_rcp_f32_e32 v97, v97
	v_add_f32_e32 v98, 1.0, v98
	v_pk_mul_f32 v[102:103], v[102:103], v[106:107] op_sel_hi:[1,0]
	v_mul_f32_e32 v100, 0xbfb8aa3b, v100
	v_mul_f32_e32 v101, 0xbfb8aa3b, v101
	v_rcp_f32_e32 v99, v99
	v_rcp_f32_e32 v98, v98
	v_mul_f32_e32 v103, 0xbfb8aa3b, v103
	v_exp_f32_e32 v100, v100
	v_exp_f32_e32 v101, v101
	v_mul_f32_e32 v102, 0xbfb8aa3b, v102
	v_exp_f32_e32 v103, v103
	v_exp_f32_e32 v102, v102
	v_fma_f32 v96, v96, s4, 0.5
	v_fma_f32 v97, v97, s4, 0.5
	v_max_f32_e32 v96, 1.0, v96
	v_max_f32_e32 v97, 1.0, v97
	v_fma_f32 v98, v98, s4, 0.5
	v_fma_f32 v99, v99, s4, 0.5
	v_add_f32_e32 v100, 1.0, v100
	v_add_f32_e32 v101, 1.0, v101
	v_cvt_u32_f32_e32 v96, v96
	v_cvt_u32_f32_e32 v97, v97
	v_max_f32_e32 v98, 1.0, v98
	v_max_f32_e32 v99, 1.0, v99
	v_add_f32_e32 v103, 1.0, v103
	v_rcp_f32_e32 v100, v100
	v_rcp_f32_e32 v101, v101
	v_cvt_u32_f32_sdwa v98, v98 dst_sel:WORD_1 dst_unused:UNUSED_PAD src0_sel:DWORD
	v_cvt_u32_f32_sdwa v99, v99 dst_sel:BYTE_3 dst_unused:UNUSED_PAD src0_sel:DWORD
	v_add_f32_e32 v102, 1.0, v102
	v_rcp_f32_e32 v103, v103
	v_rcp_f32_e32 v102, v102
	v_lshl_or_b32 v96, v97, 8, v96
	v_or3_b32 v96, v96, v98, v99
	v_fma_f32 v97, v100, s4, 0.5
	v_fma_f32 v98, v101, s4, 0.5
	v_pk_mul_f32 v[92:93], v[92:93], v[106:107] op_sel_hi:[1,0]
	v_max_f32_e32 v97, 1.0, v97
	v_max_f32_e32 v98, 1.0, v98
	v_fma_f32 v99, v102, s4, 0.5
	v_fma_f32 v100, v103, s4, 0.5
	v_mul_f32_e32 v93, 0xbfb8aa3b, v93
	v_cvt_u32_f32_e32 v97, v97
	v_cvt_u32_f32_e32 v98, v98
	v_max_f32_e32 v99, 1.0, v99
	v_max_f32_e32 v100, 1.0, v100
	v_exp_f32_e32 v93, v93
	v_cvt_u32_f32_sdwa v99, v99 dst_sel:WORD_1 dst_unused:UNUSED_PAD src0_sel:DWORD
	v_cvt_u32_f32_sdwa v100, v100 dst_sel:BYTE_3 dst_unused:UNUSED_PAD src0_sel:DWORD
	v_pk_mul_f32 v[88:89], v[88:89], v[106:107] op_sel_hi:[1,0]
	v_mul_f32_e32 v92, 0xbfb8aa3b, v92
	v_mul_f32_e32 v89, 0xbfb8aa3b, v89
	v_lshl_or_b32 v97, v98, 8, v97
	v_exp_f32_e32 v98, v92
	v_add_f32_e32 v92, 1.0, v93
	v_exp_f32_e32 v89, v89
	v_or3_b32 v97, v97, v99, v100
	v_rcp_f32_e32 v99, v92
	v_mul_f32_e32 v88, 0xbfb8aa3b, v88
	v_pk_mul_f32 v[92:93], v[94:95], v[106:107] op_sel_hi:[1,0]
	v_add_f32_e32 v94, 1.0, v98
	v_exp_f32_e32 v98, v88
	v_add_f32_e32 v88, 1.0, v89
	v_fma_f32 v95, v99, s4, 0.5
	v_rcp_f32_e32 v99, v88
	v_pk_mul_f32 v[88:89], v[90:91], v[106:107] op_sel_hi:[1,0]
	v_add_f32_e32 v90, 1.0, v98
	v_mul_f32_e32 v88, 0xbfb8aa3b, v88
	v_mul_f32_e32 v89, 0xbfb8aa3b, v89
	v_exp_f32_e32 v88, v88
	v_exp_f32_e32 v89, v89
	v_rcp_f32_e32 v90, v90
	v_fma_f32 v91, v99, s4, 0.5
	v_add_f32_e32 v88, 1.0, v88
	v_add_f32_e32 v89, 1.0, v89
	v_rcp_f32_e32 v88, v88
; __device__ __forceinline__ unsigned cvt_pk_bf16(float lo, float hi) { unsigned r; asm volatile("v_cvt_pk_bf16_f32 %0, %1, %2" : "=v"(r) : "v"(lo), "v"(hi)); return r; }
; __device__ __forceinline__ float bf_lo(unsigned w) { return __uint_as_float(w << 16); }
; __device__ __forceinline__ float bf_hi(unsigned w) { return __uint_as_float(w & 0xffff0000u); }
; #define MEMFENCE asm volatile("" ::: "memory")
; __device__ __forceinline__ float sigmoidf_(float v) { return __builtin_amdgcn_rcpf(1.0f + __expf(-v)); }
; __device__ __forceinline__ u32x4 pack8(const f32x4 a, const f32x4 b) { u32x4 w; w.x = cvt_pk_bf16(a[0], a[1]); w.y = cvt_pk_bf16(a[2], a[3]); w.z = cvt_pk_bf16(b[0], b[1]); w.w = cvt_pk_bf16(b[2], b[3]); return w; }
; __device__ __forceinline__ void unpack8(const u32x4 w, f32x4& a, f32x4& b) { a[0] = bf_lo(w.x); a[1] = bf_hi(w.x); a[2] = bf_lo(w.y); a[3] = bf_hi(w.y); b[0] = bf_lo(w.z); b[1] = bf_hi(w.z); b[2] = bf_lo(w.w); b[3] = bf_hi(w.w); }
; __device__ __forceinline__ unsigned pack4_u8c(const f32x4 v) { const unsigned q0 = (unsigned)fmaxf(v[0] * 255.0f + 0.5f, 1.0f), q1 = (unsigned)fmaxf(v[1] * 255.0f + 0.5f, 1.0f), q2 = (unsigned)fmaxf(v[2] * 255.0f + 0.5f, 1.0f), q3 = (unsigned)fmaxf(v[3] * 255.0f + 0.5f, 1.0f);
;     template <int KIND> __device__ __forceinline__ void run(f32x4 (&acc)[2][2][4][2], const Unit& u, int tid_in) const {
;     ...
;                 for (int m = 0; m < 4; ++m) { const float r = rs[ai * 4 + m] * (1.0f / GATE_WSCALE); u32x4 w;
; #pragma unroll
;                     for (int bj = 0; bj < 2; ++bj) { f32x4 a = acc[ai][bj][m][0] * r, b = acc[ai][bj][m][1] * r;
; #pragma unroll
;                         for (int j = 0; j < 4; ++j) { a[j] = sigmoidf_(a[j]); b[j] = sigmoidf_(b[j]); }
;                         if (bj == 0) { w.x = pack4_u8c(a); w.y = pack4_u8c(b); } else { w.z = pack4_u8c(a); w.w = pack4_u8c(b); } }
;                     gst[(ai * 4 + m) * 512 + tid] = w; MEMFENCE; }
	v_rcp_f32_e32 v89, v89
	v_fma_f32 v90, v90, s4, 0.5
	v_max_f32_e32 v91, 1.0, v91
	v_max_f32_e32 v90, 1.0, v90
	v_fma_f32 v88, v88, s4, 0.5
	v_fma_f32 v89, v89, s4, 0.5
	v_cvt_u32_f32_e32 v91, v91
	v_cvt_u32_f32_e32 v90, v90
	v_max_f32_e32 v88, 1.0, v88
	v_max_f32_e32 v89, 1.0, v89
	v_cvt_u32_f32_sdwa v88, v88 dst_sel:WORD_1 dst_unused:UNUSED_PAD src0_sel:DWORD
	v_cvt_u32_f32_sdwa v89, v89 dst_sel:BYTE_3 dst_unused:UNUSED_PAD src0_sel:DWORD
	v_lshl_or_b32 v90, v91, 8, v90
	v_mul_f32_e32 v108, 0xbfb8aa3b, v108
	v_mul_f32_e32 v109, 0xbfb8aa3b, v109
	v_or3_b32 v99, v90, v88, v89
	v_mul_f32_e32 v90, 0x3c800000, v141
	v_pk_mul_f32 v[80:81], v[80:81], v[90:91] op_sel_hi:[1,0]
	v_pk_mul_f32 v[82:83], v[82:83], v[90:91] op_sel_hi:[1,0]
	v_mul_f32_e32 v80, 0xbfb8aa3b, v80
	v_mul_f32_e32 v81, 0xbfb8aa3b, v81
	v_mul_f32_e32 v83, 0xbfb8aa3b, v83
	v_exp_f32_e32 v80, v80
	v_exp_f32_e32 v81, v81
	v_mul_f32_e32 v82, 0xbfb8aa3b, v82
	v_exp_f32_e32 v83, v83
	v_exp_f32_e32 v82, v82
	v_add_f32_e32 v80, 1.0, v80
	v_add_f32_e32 v81, 1.0, v81
	v_pk_mul_f32 v[84:85], v[84:85], v[90:91] op_sel_hi:[1,0]
	v_add_f32_e32 v83, 1.0, v83
	v_rcp_f32_e32 v80, v80
	v_rcp_f32_e32 v81, v81
	v_add_f32_e32 v82, 1.0, v82
	v_pk_mul_f32 v[86:87], v[86:87], v[90:91] op_sel_hi:[1,0]
	v_mul_f32_e32 v84, 0xbfb8aa3b, v84
	v_mul_f32_e32 v85, 0xbfb8aa3b, v85
	v_rcp_f32_e32 v83, v83
	v_rcp_f32_e32 v82, v82
	v_mul_f32_e32 v87, 0xbfb8aa3b, v87
	v_exp_f32_e32 v84, v84
	v_exp_f32_e32 v85, v85
	v_mul_f32_e32 v86, 0xbfb8aa3b, v86
	v_exp_f32_e32 v87, v87
	v_exp_f32_e32 v86, v86
	v_fma_f32 v80, v80, s4, 0.5
	v_fma_f32 v81, v81, s4, 0.5
	v_max_f32_e32 v80, 1.0, v80
	v_max_f32_e32 v81, 1.0, v81
	v_fma_f32 v82, v82, s4, 0.5
	v_fma_f32 v83, v83, s4, 0.5
	v_add_f32_e32 v84, 1.0, v84
	v_add_f32_e32 v85, 1.0, v85
	v_cvt_u32_f32_e32 v80, v80
	v_cvt_u32_f32_e32 v81, v81
	v_max_f32_e32 v82, 1.0, v82
	v_max_f32_e32 v83, 1.0, v83
	v_add_f32_e32 v87, 1.0, v87
	v_rcp_f32_e32 v84, v84
	v_rcp_f32_e32 v85, v85
	v_cvt_u32_f32_sdwa v82, v82 dst_sel:WORD_1 dst_unused:UNUSED_PAD src0_sel:DWORD
	v_cvt_u32_f32_sdwa v83, v83 dst_sel:BYTE_3 dst_unused:UNUSED_PAD src0_sel:DWORD
	v_add_f32_e32 v86, 1.0, v86
	v_rcp_f32_e32 v87, v87
	v_rcp_f32_e32 v86, v86
	v_lshl_or_b32 v80, v81, 8, v80
	v_or3_b32 v80, v80, v82, v83
	v_fma_f32 v81, v84, s4, 0.5
	v_fma_f32 v82, v85, s4, 0.5
	v_pk_mul_f32 v[76:77], v[76:77], v[90:91] op_sel_hi:[1,0]
	v_max_f32_e32 v81, 1.0, v81
	v_max_f32_e32 v82, 1.0, v82
	v_fma_f32 v83, v86, s4, 0.5
	v_fma_f32 v84, v87, s4, 0.5
	v_mul_f32_e32 v77, 0xbfb8aa3b, v77
	v_cvt_u32_f32_e32 v81, v81
	v_cvt_u32_f32_e32 v82, v82
	v_max_f32_e32 v83, 1.0, v83
	v_max_f32_e32 v84, 1.0, v84
	v_exp_f32_e32 v77, v77
	v_cvt_u32_f32_sdwa v83, v83 dst_sel:WORD_1 dst_unused:UNUSED_PAD src0_sel:DWORD
	v_cvt_u32_f32_sdwa v84, v84 dst_sel:BYTE_3 dst_unused:UNUSED_PAD src0_sel:DWORD
	v_pk_mul_f32 v[72:73], v[72:73], v[90:91] op_sel_hi:[1,0]
	v_mul_f32_e32 v76, 0xbfb8aa3b, v76
	v_mul_f32_e32 v73, 0xbfb8aa3b, v73
	v_lshl_or_b32 v81, v82, 8, v81
	v_exp_f32_e32 v82, v76
	v_add_f32_e32 v76, 1.0, v77
	v_exp_f32_e32 v73, v73
	v_or3_b32 v81, v81, v83, v84
	v_rcp_f32_e32 v83, v76
	v_mul_f32_e32 v72, 0xbfb8aa3b, v72
	v_pk_mul_f32 v[76:77], v[78:79], v[90:91] op_sel_hi:[1,0]
	v_add_f32_e32 v78, 1.0, v82
	v_exp_f32_e32 v82, v72
	v_add_f32_e32 v72, 1.0, v73
	v_fma_f32 v79, v83, s4, 0.5
	v_rcp_f32_e32 v83, v72
	v_pk_mul_f32 v[72:73], v[74:75], v[90:91] op_sel_hi:[1,0]
	v_add_f32_e32 v74, 1.0, v82
	v_mul_f32_e32 v72, 0xbfb8aa3b, v72
	v_mul_f32_e32 v73, 0xbfb8aa3b, v73
	v_exp_f32_e32 v72, v72
	v_exp_f32_e32 v73, v73
	v_rcp_f32_e32 v74, v74
	v_fma_f32 v75, v83, s4, 0.5
	v_add_f32_e32 v72, 1.0, v72
	v_add_f32_e32 v73, 1.0, v73
	v_rcp_f32_e32 v72, v72
	v_rcp_f32_e32 v73, v73
	v_fma_f32 v74, v74, s4, 0.5
	v_max_f32_e32 v75, 1.0, v75
	v_max_f32_e32 v74, 1.0, v74
	v_fma_f32 v72, v72, s4, 0.5
	v_fma_f32 v73, v73, s4, 0.5
	v_cvt_u32_f32_e32 v75, v75
	v_cvt_u32_f32_e32 v74, v74
	v_max_f32_e32 v72, 1.0, v72
	v_max_f32_e32 v73, 1.0, v73
	v_cvt_u32_f32_sdwa v72, v72 dst_sel:WORD_1 dst_unused:UNUSED_PAD src0_sel:DWORD
	v_cvt_u32_f32_sdwa v73, v73 dst_sel:BYTE_3 dst_unused:UNUSED_PAD src0_sel:DWORD
	v_lshl_or_b32 v74, v75, 8, v74
	v_exp_f32_e32 v108, v108
	v_exp_f32_e32 v109, v109
	v_or3_b32 v83, v74, v72, v73
	v_mul_f32_e32 v74, 0x3c800000, v138
	v_pk_mul_f32 v[64:65], v[64:65], v[74:75] op_sel_hi:[1,0]
	v_pk_mul_f32 v[66:67], v[66:67], v[74:75] op_sel_hi:[1,0]
	v_mul_f32_e32 v64, 0xbfb8aa3b, v64
	v_mul_f32_e32 v65, 0xbfb8aa3b, v65
	v_mul_f32_e32 v67, 0xbfb8aa3b, v67
	v_exp_f32_e32 v64, v64
	v_exp_f32_e32 v65, v65
	v_mul_f32_e32 v66, 0xbfb8aa3b, v66
	v_exp_f32_e32 v67, v67
	v_exp_f32_e32 v66, v66
	v_add_f32_e32 v64, 1.0, v64
	v_add_f32_e32 v65, 1.0, v65
	v_pk_mul_f32 v[68:69], v[68:69], v[74:75] op_sel_hi:[1,0]
	v_add_f32_e32 v67, 1.0, v67
	v_rcp_f32_e32 v64, v64
	v_rcp_f32_e32 v65, v65
	v_add_f32_e32 v66, 1.0, v66
	v_pk_mul_f32 v[70:71], v[70:71], v[74:75] op_sel_hi:[1,0]
	v_mul_f32_e32 v68, 0xbfb8aa3b, v68
	v_mul_f32_e32 v69, 0xbfb8aa3b, v69
	v_rcp_f32_e32 v67, v67
	v_rcp_f32_e32 v66, v66
	v_mul_f32_e32 v71, 0xbfb8aa3b, v71
	v_exp_f32_e32 v68, v68
	v_exp_f32_e32 v69, v69
	v_mul_f32_e32 v70, 0xbfb8aa3b, v70
	v_exp_f32_e32 v71, v71
	v_exp_f32_e32 v70, v70
	v_fma_f32 v64, v64, s4, 0.5
	v_fma_f32 v65, v65, s4, 0.5
	v_max_f32_e32 v64, 1.0, v64
	v_max_f32_e32 v65, 1.0, v65
	v_fma_f32 v66, v66, s4, 0.5
	v_fma_f32 v67, v67, s4, 0.5
	v_add_f32_e32 v68, 1.0, v68
	v_add_f32_e32 v69, 1.0, v69
	v_cvt_u32_f32_e32 v64, v64
	v_cvt_u32_f32_e32 v65, v65
	v_max_f32_e32 v66, 1.0, v66
	v_max_f32_e32 v67, 1.0, v67
	v_add_f32_e32 v71, 1.0, v71
	v_rcp_f32_e32 v68, v68
; __device__ __forceinline__ unsigned cvt_pk_bf16(float lo, float hi) { unsigned r; asm volatile("v_cvt_pk_bf16_f32 %0, %1, %2" : "=v"(r) : "v"(lo), "v"(hi)); return r; }
; __device__ __forceinline__ float bf_lo(unsigned w) { return __uint_as_float(w << 16); }
; __device__ __forceinline__ float bf_hi(unsigned w) { return __uint_as_float(w & 0xffff0000u); }
; #define MEMFENCE asm volatile("" ::: "memory")
; __device__ __forceinline__ float sigmoidf_(float v) { return __builtin_amdgcn_rcpf(1.0f + __expf(-v)); }
; __device__ __forceinline__ u32x4 pack8(const f32x4 a, const f32x4 b) { u32x4 w; w.x = cvt_pk_bf16(a[0], a[1]); w.y = cvt_pk_bf16(a[2], a[3]); w.z = cvt_pk_bf16(b[0], b[1]); w.w = cvt_pk_bf16(b[2], b[3]); return w; }
; __device__ __forceinline__ void unpack8(const u32x4 w, f32x4& a, f32x4& b) { a[0] = bf_lo(w.x); a[1] = bf_hi(w.x); a[2] = bf_lo(w.y); a[3] = bf_hi(w.y); b[0] = bf_lo(w.z); b[1] = bf_hi(w.z); b[2] = bf_lo(w.w); b[3] = bf_hi(w.w); }
; __device__ __forceinline__ unsigned pack4_u8c(const f32x4 v) { const unsigned q0 = (unsigned)fmaxf(v[0] * 255.0f + 0.5f, 1.0f), q1 = (unsigned)fmaxf(v[1] * 255.0f + 0.5f, 1.0f), q2 = (unsigned)fmaxf(v[2] * 255.0f + 0.5f, 1.0f), q3 = (unsigned)fmaxf(v[3] * 255.0f + 0.5f, 1.0f);
;     template <int KIND> __device__ __forceinline__ void run(f32x4 (&acc)[2][2][4][2], const Unit& u, int tid_in) const {
;     ...
;                 for (int m = 0; m < 4; ++m) { const float r = rs[ai * 4 + m] * (1.0f / GATE_WSCALE); u32x4 w;
; #pragma unroll
;                     for (int bj = 0; bj < 2; ++bj) { f32x4 a = acc[ai][bj][m][0] * r, b = acc[ai][bj][m][1] * r;
; #pragma unroll
;                         for (int j = 0; j < 4; ++j) { a[j] = sigmoidf_(a[j]); b[j] = sigmoidf_(b[j]); }
;                         if (bj == 0) { w.x = pack4_u8c(a); w.y = pack4_u8c(b); } else { w.z = pack4_u8c(a); w.w = pack4_u8c(b); } }
;                     gst[(ai * 4 + m) * 512 + tid] = w; MEMFENCE; }
	v_rcp_f32_e32 v69, v69
	v_cvt_u32_f32_sdwa v66, v66 dst_sel:WORD_1 dst_unused:UNUSED_PAD src0_sel:DWORD
	v_cvt_u32_f32_sdwa v67, v67 dst_sel:BYTE_3 dst_unused:UNUSED_PAD src0_sel:DWORD
	v_add_f32_e32 v70, 1.0, v70
	v_rcp_f32_e32 v71, v71
	v_rcp_f32_e32 v70, v70
	v_lshl_or_b32 v64, v65, 8, v64
	v_or3_b32 v64, v64, v66, v67
	v_fma_f32 v65, v68, s4, 0.5
	v_fma_f32 v66, v69, s4, 0.5
	v_pk_mul_f32 v[60:61], v[60:61], v[74:75] op_sel_hi:[1,0]
	v_max_f32_e32 v65, 1.0, v65
	v_max_f32_e32 v66, 1.0, v66
	v_fma_f32 v67, v70, s4, 0.5
	v_fma_f32 v68, v71, s4, 0.5
	v_mul_f32_e32 v61, 0xbfb8aa3b, v61
	v_cvt_u32_f32_e32 v65, v65
	v_cvt_u32_f32_e32 v66, v66
	v_max_f32_e32 v67, 1.0, v67
	v_max_f32_e32 v68, 1.0, v68
	v_exp_f32_e32 v61, v61
	v_cvt_u32_f32_sdwa v67, v67 dst_sel:WORD_1 dst_unused:UNUSED_PAD src0_sel:DWORD
	v_cvt_u32_f32_sdwa v68, v68 dst_sel:BYTE_3 dst_unused:UNUSED_PAD src0_sel:DWORD
	v_pk_mul_f32 v[56:57], v[56:57], v[74:75] op_sel_hi:[1,0]
	v_mul_f32_e32 v60, 0xbfb8aa3b, v60
	v_mul_f32_e32 v57, 0xbfb8aa3b, v57
	v_lshl_or_b32 v65, v66, 8, v65
	v_exp_f32_e32 v66, v60
	v_add_f32_e32 v60, 1.0, v61
	v_exp_f32_e32 v57, v57
	v_or3_b32 v65, v65, v67, v68
	v_rcp_f32_e32 v67, v60
	v_mul_f32_e32 v56, 0xbfb8aa3b, v56
	v_pk_mul_f32 v[60:61], v[62:63], v[74:75] op_sel_hi:[1,0]
	v_add_f32_e32 v62, 1.0, v66
	v_exp_f32_e32 v66, v56
	v_add_f32_e32 v56, 1.0, v57
	v_fma_f32 v63, v67, s4, 0.5
	v_rcp_f32_e32 v67, v56
	v_pk_mul_f32 v[56:57], v[58:59], v[74:75] op_sel_hi:[1,0]
	v_add_f32_e32 v58, 1.0, v66
	v_mul_f32_e32 v56, 0xbfb8aa3b, v56
	v_mul_f32_e32 v57, 0xbfb8aa3b, v57
	v_exp_f32_e32 v56, v56
	v_exp_f32_e32 v57, v57
	v_rcp_f32_e32 v58, v58
	v_fma_f32 v59, v67, s4, 0.5
	v_add_f32_e32 v56, 1.0, v56
	v_add_f32_e32 v57, 1.0, v57
	v_rcp_f32_e32 v56, v56
	v_rcp_f32_e32 v57, v57
	v_fma_f32 v58, v58, s4, 0.5
	v_max_f32_e32 v59, 1.0, v59
	v_max_f32_e32 v58, 1.0, v58
	v_fma_f32 v56, v56, s4, 0.5
	v_fma_f32 v57, v57, s4, 0.5
	v_cvt_u32_f32_e32 v59, v59
	v_cvt_u32_f32_e32 v58, v58
	v_max_f32_e32 v56, 1.0, v56
	v_max_f32_e32 v57, 1.0, v57
	v_cvt_u32_f32_sdwa v56, v56 dst_sel:WORD_1 dst_unused:UNUSED_PAD src0_sel:DWORD
	v_cvt_u32_f32_sdwa v57, v57 dst_sel:BYTE_3 dst_unused:UNUSED_PAD src0_sel:DWORD
	v_lshl_or_b32 v58, v59, 8, v58
	v_mul_f32_e32 v92, 0xbfb8aa3b, v92
	v_mul_f32_e32 v93, 0xbfb8aa3b, v93
	v_or3_b32 v67, v58, v56, v57
	v_mul_f32_e32 v58, 0x3c800000, v139
	v_pk_mul_f32 v[48:49], v[48:49], v[58:59] op_sel_hi:[1,0]
	v_pk_mul_f32 v[50:51], v[50:51], v[58:59] op_sel_hi:[1,0]
	v_mul_f32_e32 v48, 0xbfb8aa3b, v48
	v_mul_f32_e32 v49, 0xbfb8aa3b, v49
	v_mul_f32_e32 v51, 0xbfb8aa3b, v51
	v_exp_f32_e32 v48, v48
	v_exp_f32_e32 v49, v49
	v_mul_f32_e32 v50, 0xbfb8aa3b, v50
	v_exp_f32_e32 v51, v51
	v_exp_f32_e32 v50, v50
	v_add_f32_e32 v48, 1.0, v48
	v_add_f32_e32 v49, 1.0, v49
	v_pk_mul_f32 v[52:53], v[52:53], v[58:59] op_sel_hi:[1,0]
	v_add_f32_e32 v51, 1.0, v51
	v_rcp_f32_e32 v48, v48
	v_rcp_f32_e32 v49, v49
	v_add_f32_e32 v50, 1.0, v50
	v_pk_mul_f32 v[54:55], v[54:55], v[58:59] op_sel_hi:[1,0]
	v_mul_f32_e32 v52, 0xbfb8aa3b, v52
	v_mul_f32_e32 v53, 0xbfb8aa3b, v53
	v_rcp_f32_e32 v51, v51
	v_rcp_f32_e32 v50, v50
	v_mul_f32_e32 v55, 0xbfb8aa3b, v55
	v_exp_f32_e32 v52, v52
	v_exp_f32_e32 v53, v53
	v_mul_f32_e32 v54, 0xbfb8aa3b, v54
	v_exp_f32_e32 v55, v55
	v_exp_f32_e32 v54, v54
	v_fma_f32 v48, v48, s4, 0.5
	v_fma_f32 v49, v49, s4, 0.5
	v_max_f32_e32 v48, 1.0, v48
	v_max_f32_e32 v49, 1.0, v49
	v_fma_f32 v50, v50, s4, 0.5
	v_fma_f32 v51, v51, s4, 0.5
	v_add_f32_e32 v52, 1.0, v52
	v_add_f32_e32 v53, 1.0, v53
	v_cvt_u32_f32_e32 v48, v48
	v_cvt_u32_f32_e32 v49, v49
	v_max_f32_e32 v50, 1.0, v50
	v_max_f32_e32 v51, 1.0, v51
	v_add_f32_e32 v55, 1.0, v55
	v_rcp_f32_e32 v52, v52
	v_rcp_f32_e32 v53, v53
	v_cvt_u32_f32_sdwa v50, v50 dst_sel:WORD_1 dst_unused:UNUSED_PAD src0_sel:DWORD
	v_cvt_u32_f32_sdwa v51, v51 dst_sel:BYTE_3 dst_unused:UNUSED_PAD src0_sel:DWORD
	v_add_f32_e32 v54, 1.0, v54
	v_rcp_f32_e32 v55, v55
	v_rcp_f32_e32 v54, v54
	v_lshl_or_b32 v48, v49, 8, v48
	v_or3_b32 v48, v48, v50, v51
	v_fma_f32 v49, v52, s4, 0.5
	v_fma_f32 v50, v53, s4, 0.5
	v_pk_mul_f32 v[44:45], v[44:45], v[58:59] op_sel_hi:[1,0]
	v_max_f32_e32 v49, 1.0, v49
	v_max_f32_e32 v50, 1.0, v50
	v_fma_f32 v51, v54, s4, 0.5
	v_fma_f32 v52, v55, s4, 0.5
	v_mul_f32_e32 v45, 0xbfb8aa3b, v45
	v_cvt_u32_f32_e32 v49, v49
	v_cvt_u32_f32_e32 v50, v50
	v_max_f32_e32 v51, 1.0, v51
	v_max_f32_e32 v52, 1.0, v52
	v_exp_f32_e32 v45, v45
	v_cvt_u32_f32_sdwa v51, v51 dst_sel:WORD_1 dst_unused:UNUSED_PAD src0_sel:DWORD
	v_cvt_u32_f32_sdwa v52, v52 dst_sel:BYTE_3 dst_unused:UNUSED_PAD src0_sel:DWORD
	v_pk_mul_f32 v[40:41], v[40:41], v[58:59] op_sel_hi:[1,0]
	v_mul_f32_e32 v44, 0xbfb8aa3b, v44
	v_mul_f32_e32 v41, 0xbfb8aa3b, v41
	v_lshl_or_b32 v49, v50, 8, v49
	v_exp_f32_e32 v50, v44
	v_add_f32_e32 v44, 1.0, v45
	v_exp_f32_e32 v41, v41
	v_or3_b32 v49, v49, v51, v52
	v_rcp_f32_e32 v51, v44
	v_mul_f32_e32 v40, 0xbfb8aa3b, v40
	v_pk_mul_f32 v[44:45], v[46:47], v[58:59] op_sel_hi:[1,0]
	v_add_f32_e32 v46, 1.0, v50
	v_exp_f32_e32 v50, v40
	v_add_f32_e32 v40, 1.0, v41
	v_fma_f32 v47, v51, s4, 0.5
	v_rcp_f32_e32 v51, v40
	v_pk_mul_f32 v[40:41], v[42:43], v[58:59] op_sel_hi:[1,0]
	v_add_f32_e32 v42, 1.0, v50
	v_mul_f32_e32 v40, 0xbfb8aa3b, v40
	v_mul_f32_e32 v41, 0xbfb8aa3b, v41
	v_exp_f32_e32 v40, v40
	v_exp_f32_e32 v41, v41
	v_rcp_f32_e32 v42, v42
	v_fma_f32 v43, v51, s4, 0.5
	v_add_f32_e32 v40, 1.0, v40
	v_add_f32_e32 v41, 1.0, v41
	v_rcp_f32_e32 v40, v40
	v_rcp_f32_e32 v41, v41
	v_fma_f32 v42, v42, s4, 0.5
	v_max_f32_e32 v43, 1.0, v43
	v_max_f32_e32 v42, 1.0, v42
	v_fma_f32 v40, v40, s4, 0.5
	v_fma_f32 v41, v41, s4, 0.5
; __device__ __forceinline__ float sigmoidf_(float v) { return __builtin_amdgcn_rcpf(1.0f + __expf(-v)); }
; #define MEMFENCE asm volatile("" ::: "memory")
;     template <int KIND> __device__ __forceinline__ void run(f32x4 (&acc)[2][2][4][2], const Unit& u, int tid_in) const {
;     ...
;             u32x4* gst = (u32x4*)((unsigned char*)x + 32 * MiB) + ((size_t)(blockIdx.x * 2 + (u.ord & 1)) * 3 + u.aux) * 4096;
; #pragma unroll
;             for (int ai = 0; ai < 2; ++ai)
; #pragma unroll
;                 for (int m = 0; m < 4; ++m) { const float r = rs[ai * 4 + m] * (1.0f / GATE_WSCALE); u32x4 w;
; #pragma unroll
;                     for (int bj = 0; bj < 2; ++bj) { f32x4 a = acc[ai][bj][m][0] * r, b = acc[ai][bj][m][1] * r;
; #pragma unroll
;                         for (int j = 0; j < 4; ++j) { a[j] = sigmoidf_(a[j]); b[j] = sigmoidf_(b[j]); }
;                         if (bj == 0) { w.x = pack4_u8c(a); w.y = pack4_u8c(b); } else { w.z = pack4_u8c(a); w.w = pack4_u8c(b); } }
;                     gst[(ai * 4 + m) * 512 + tid] = w; MEMFENCE; }
	v_cvt_u32_f32_e32 v43, v43
	v_cvt_u32_f32_e32 v42, v42
	v_max_f32_e32 v40, 1.0, v40
	v_max_f32_e32 v41, 1.0, v41
	v_cvt_u32_f32_sdwa v40, v40 dst_sel:WORD_1 dst_unused:UNUSED_PAD src0_sel:DWORD
	v_cvt_u32_f32_sdwa v41, v41 dst_sel:BYTE_3 dst_unused:UNUSED_PAD src0_sel:DWORD
	v_lshl_or_b32 v42, v43, 8, v42
	v_exp_f32_e32 v92, v92
	v_exp_f32_e32 v93, v93
	v_or3_b32 v51, v42, v40, v41
	v_mul_f32_e32 v42, 0x3c800000, v136
	v_pk_mul_f32 v[32:33], v[32:33], v[42:43] op_sel_hi:[1,0]
	v_pk_mul_f32 v[34:35], v[34:35], v[42:43] op_sel_hi:[1,0]
	v_mul_f32_e32 v32, 0xbfb8aa3b, v32
	v_mul_f32_e32 v33, 0xbfb8aa3b, v33
	v_mul_f32_e32 v35, 0xbfb8aa3b, v35
	v_exp_f32_e32 v32, v32
	v_exp_f32_e32 v33, v33
	v_mul_f32_e32 v34, 0xbfb8aa3b, v34
	v_exp_f32_e32 v35, v35
	v_exp_f32_e32 v34, v34
	v_add_f32_e32 v32, 1.0, v32
	v_add_f32_e32 v33, 1.0, v33
	v_pk_mul_f32 v[36:37], v[36:37], v[42:43] op_sel_hi:[1,0]
	v_add_f32_e32 v35, 1.0, v35
	v_rcp_f32_e32 v32, v32
	v_rcp_f32_e32 v33, v33
	v_add_f32_e32 v34, 1.0, v34
	v_pk_mul_f32 v[38:39], v[38:39], v[42:43] op_sel_hi:[1,0]
	v_mul_f32_e32 v36, 0xbfb8aa3b, v36
	v_mul_f32_e32 v37, 0xbfb8aa3b, v37
	v_rcp_f32_e32 v35, v35
	v_rcp_f32_e32 v34, v34
	v_mul_f32_e32 v39, 0xbfb8aa3b, v39
	v_exp_f32_e32 v36, v36
	v_exp_f32_e32 v37, v37
	v_mul_f32_e32 v38, 0xbfb8aa3b, v38
	v_exp_f32_e32 v39, v39
	v_exp_f32_e32 v38, v38
	v_fma_f32 v32, v32, s4, 0.5
	v_fma_f32 v33, v33, s4, 0.5
	v_max_f32_e32 v32, 1.0, v32
	v_max_f32_e32 v33, 1.0, v33
	v_fma_f32 v34, v34, s4, 0.5
	v_fma_f32 v35, v35, s4, 0.5
	v_add_f32_e32 v36, 1.0, v36
	v_add_f32_e32 v37, 1.0, v37
	v_cvt_u32_f32_e32 v32, v32
	v_cvt_u32_f32_e32 v33, v33
	v_max_f32_e32 v34, 1.0, v34
	v_max_f32_e32 v35, 1.0, v35
	v_add_f32_e32 v39, 1.0, v39
	v_rcp_f32_e32 v36, v36
	v_rcp_f32_e32 v37, v37
	v_cvt_u32_f32_sdwa v34, v34 dst_sel:WORD_1 dst_unused:UNUSED_PAD src0_sel:DWORD
	v_cvt_u32_f32_sdwa v35, v35 dst_sel:BYTE_3 dst_unused:UNUSED_PAD src0_sel:DWORD
	v_add_f32_e32 v38, 1.0, v38
	v_rcp_f32_e32 v39, v39
	v_rcp_f32_e32 v38, v38
	v_lshl_or_b32 v32, v33, 8, v32
	v_or3_b32 v32, v32, v34, v35
	v_fma_f32 v33, v36, s4, 0.5
	v_fma_f32 v34, v37, s4, 0.5
	v_pk_mul_f32 v[28:29], v[28:29], v[42:43] op_sel_hi:[1,0]
	v_max_f32_e32 v33, 1.0, v33
	v_max_f32_e32 v34, 1.0, v34
	v_fma_f32 v35, v38, s4, 0.5
	v_fma_f32 v36, v39, s4, 0.5
	v_mul_f32_e32 v29, 0xbfb8aa3b, v29
	v_cvt_u32_f32_e32 v33, v33
	v_cvt_u32_f32_e32 v34, v34
	v_max_f32_e32 v35, 1.0, v35
	v_max_f32_e32 v36, 1.0, v36
	v_exp_f32_e32 v29, v29
	v_cvt_u32_f32_sdwa v35, v35 dst_sel:WORD_1 dst_unused:UNUSED_PAD src0_sel:DWORD
	v_cvt_u32_f32_sdwa v36, v36 dst_sel:BYTE_3 dst_unused:UNUSED_PAD src0_sel:DWORD
	v_pk_mul_f32 v[24:25], v[24:25], v[42:43] op_sel_hi:[1,0]
	v_mul_f32_e32 v28, 0xbfb8aa3b, v28
	v_mul_f32_e32 v25, 0xbfb8aa3b, v25
	v_lshl_or_b32 v33, v34, 8, v33
	v_exp_f32_e32 v34, v28
	v_add_f32_e32 v28, 1.0, v29
	v_exp_f32_e32 v25, v25
	v_or3_b32 v33, v33, v35, v36
	v_rcp_f32_e32 v35, v28
	v_mul_f32_e32 v24, 0xbfb8aa3b, v24
	v_mul_f32_e32 v76, 0xbfb8aa3b, v76
	v_mul_f32_e32 v77, 0xbfb8aa3b, v77
	v_pk_mul_f32 v[28:29], v[30:31], v[42:43] op_sel_hi:[1,0]
	v_add_f32_e32 v30, 1.0, v34
	v_exp_f32_e32 v34, v24
	v_add_f32_e32 v24, 1.0, v25
	v_exp_f32_e32 v76, v76
	v_exp_f32_e32 v77, v77
	v_mul_f32_e32 v60, 0xbfb8aa3b, v60
	v_mul_f32_e32 v61, 0xbfb8aa3b, v61
	v_fma_f32 v31, v35, s4, 0.5
	v_rcp_f32_e32 v35, v24
	v_pk_mul_f32 v[24:25], v[26:27], v[42:43] op_sel_hi:[1,0]
	v_rcp_f32_e32 v126, v126
	v_add_f32_e32 v124, 1.0, v124
	v_add_f32_e32 v125, 1.0, v125
	v_exp_f32_e32 v60, v60
	v_exp_f32_e32 v61, v61
	v_mul_f32_e32 v44, 0xbfb8aa3b, v44
	v_mul_f32_e32 v45, 0xbfb8aa3b, v45
	v_mul_f32_e32 v24, 0xbfb8aa3b, v24
	v_mul_f32_e32 v25, 0xbfb8aa3b, v25
	v_rcp_f32_e32 v124, v124
	v_rcp_f32_e32 v125, v125
	v_rcp_f32_e32 v110, v110
	v_add_f32_e32 v108, 1.0, v108
	v_add_f32_e32 v109, 1.0, v109
	v_exp_f32_e32 v44, v44
	v_exp_f32_e32 v45, v45
	v_mul_f32_e32 v28, 0xbfb8aa3b, v28
	v_mul_f32_e32 v29, 0xbfb8aa3b, v29
	v_exp_f32_e32 v24, v24
	v_exp_f32_e32 v25, v25
	s_lshl_b64 s[2:3], s[2:3], 16
	v_rcp_f32_e32 v108, v108
	v_rcp_f32_e32 v109, v109
	v_rcp_f32_e32 v94, v94
	v_add_f32_e32 v92, 1.0, v92
	v_add_f32_e32 v93, 1.0, v93
	v_exp_f32_e32 v28, v28
	v_exp_f32_e32 v29, v29
	s_add_u32 s2, s29, s2
	v_rcp_f32_e32 v92, v92
	v_rcp_f32_e32 v93, v93
	v_rcp_f32_e32 v78, v78
	v_add_f32_e32 v76, 1.0, v76
	v_add_f32_e32 v77, 1.0, v77
	s_addc_u32 s3, s30, s3
	v_fma_f32 v126, v126, s4, 0.5
	v_ashrrev_i32_e32 v143, 31, v142
	v_rcp_f32_e32 v76, v76
	v_rcp_f32_e32 v77, v77
	v_rcp_f32_e32 v62, v62
	v_add_f32_e32 v60, 1.0, v60
	v_add_f32_e32 v61, 1.0, v61
	v_add_f32_e32 v26, 1.0, v34
	v_max_f32_e32 v127, 1.0, v127
	v_max_f32_e32 v126, 1.0, v126
	v_fma_f32 v124, v124, s4, 0.5
	v_fma_f32 v125, v125, s4, 0.5
	v_lshl_add_u64 v[120:121], v[142:143], 4, s[2:3]
	v_fma_f32 v110, v110, s4, 0.5
	s_movk_i32 s2, 0x2000
	v_rcp_f32_e32 v60, v60
	v_rcp_f32_e32 v61, v61
	v_rcp_f32_e32 v46, v46
	v_add_f32_e32 v44, 1.0, v44
	v_add_f32_e32 v45, 1.0, v45
	v_rcp_f32_e32 v26, v26
	v_add_f32_e32 v24, 1.0, v24
	v_add_f32_e32 v25, 1.0, v25
	v_cvt_u32_f32_e32 v127, v127
	v_cvt_u32_f32_e32 v126, v126
	v_max_f32_e32 v124, 1.0, v124
	v_max_f32_e32 v125, 1.0, v125
	v_max_f32_e32 v111, 1.0, v111
	v_max_f32_e32 v110, 1.0, v110
	v_fma_f32 v108, v108, s4, 0.5
	v_fma_f32 v109, v109, s4, 0.5
	v_add_co_u32_e32 v104, vcc, s2, v120
	v_fma_f32 v94, v94, s4, 0.5
	v_rcp_f32_e32 v44, v44
	v_rcp_f32_e32 v45, v45
	v_rcp_f32_e32 v30, v30
	v_add_f32_e32 v28, 1.0, v28
	v_add_f32_e32 v29, 1.0, v29
	v_rcp_f32_e32 v24, v24
	v_rcp_f32_e32 v25, v25
	v_cvt_u32_f32_sdwa v124, v124 dst_sel:WORD_1 dst_unused:UNUSED_PAD src0_sel:DWORD
; #define MEMFENCE asm volatile("" ::: "memory")
;     template <int KIND> __device__ __forceinline__ void run(f32x4 (&acc)[2][2][4][2], const Unit& u, int tid_in) const {
;     ...
;                     gst[(ai * 4 + m) * 512 + tid] = w; MEMFENCE; }
	v_cvt_u32_f32_sdwa v125, v125 dst_sel:BYTE_3 dst_unused:UNUSED_PAD src0_sel:DWORD
	v_cvt_u32_f32_e32 v111, v111
	v_cvt_u32_f32_e32 v110, v110
	v_max_f32_e32 v108, 1.0, v108
	v_max_f32_e32 v109, 1.0, v109
	v_addc_co_u32_e32 v105, vcc, 0, v121, vcc
	v_max_f32_e32 v95, 1.0, v95
	v_max_f32_e32 v94, 1.0, v94
	v_fma_f32 v92, v92, s4, 0.5
	v_fma_f32 v93, v93, s4, 0.5
	v_fma_f32 v78, v78, s4, 0.5
	v_rcp_f32_e32 v28, v28
	v_rcp_f32_e32 v29, v29
	v_cvt_u32_f32_sdwa v108, v108 dst_sel:WORD_1 dst_unused:UNUSED_PAD src0_sel:DWORD
	v_cvt_u32_f32_sdwa v109, v109 dst_sel:BYTE_3 dst_unused:UNUSED_PAD src0_sel:DWORD
	v_cvt_u32_f32_e32 v95, v95
	v_cvt_u32_f32_e32 v94, v94
	v_max_f32_e32 v92, 1.0, v92
	v_max_f32_e32 v93, 1.0, v93
	v_add_co_u32_e32 v88, vcc, s49, v120
	v_max_f32_e32 v79, 1.0, v79
	v_max_f32_e32 v78, 1.0, v78
	v_fma_f32 v76, v76, s4, 0.5
	v_fma_f32 v77, v77, s4, 0.5
	v_fma_f32 v62, v62, s4, 0.5
	v_cvt_u32_f32_sdwa v92, v92 dst_sel:WORD_1 dst_unused:UNUSED_PAD src0_sel:DWORD
	v_cvt_u32_f32_sdwa v93, v93 dst_sel:BYTE_3 dst_unused:UNUSED_PAD src0_sel:DWORD
	v_addc_co_u32_e32 v89, vcc, 0, v121, vcc
	v_cvt_u32_f32_e32 v79, v79
	v_cvt_u32_f32_e32 v78, v78
	v_max_f32_e32 v76, 1.0, v76
	v_max_f32_e32 v77, 1.0, v77
	s_movk_i32 s2, 0x6000
	v_max_f32_e32 v63, 1.0, v63
	v_max_f32_e32 v62, 1.0, v62
	v_fma_f32 v60, v60, s4, 0.5
	v_fma_f32 v61, v61, s4, 0.5
	v_fma_f32 v46, v46, s4, 0.5
	v_fma_f32 v27, v35, s4, 0.5
	v_fma_f32 v26, v26, s4, 0.5
	v_lshl_or_b32 v126, v127, 8, v126
	v_cvt_u32_f32_sdwa v76, v76 dst_sel:WORD_1 dst_unused:UNUSED_PAD src0_sel:DWORD
	v_cvt_u32_f32_sdwa v77, v77 dst_sel:BYTE_3 dst_unused:UNUSED_PAD src0_sel:DWORD
	v_add_co_u32_e32 v72, vcc, s2, v120
	v_cvt_u32_f32_e32 v63, v63
	v_cvt_u32_f32_e32 v62, v62
	v_max_f32_e32 v60, 1.0, v60
	v_max_f32_e32 v61, 1.0, v61
	v_max_f32_e32 v47, 1.0, v47
	v_max_f32_e32 v46, 1.0, v46
	v_fma_f32 v44, v44, s4, 0.5
	v_fma_f32 v45, v45, s4, 0.5
	v_fma_f32 v30, v30, s4, 0.5
	v_max_f32_e32 v27, 1.0, v27
	v_max_f32_e32 v26, 1.0, v26
	v_fma_f32 v24, v24, s4, 0.5
	v_fma_f32 v25, v25, s4, 0.5
	v_or3_b32 v130, v126, v124, v125
	v_lshl_or_b32 v110, v111, 8, v110
	v_addc_co_u32_e32 v73, vcc, 0, v121, vcc
	v_cvt_u32_f32_sdwa v60, v60 dst_sel:WORD_1 dst_unused:UNUSED_PAD src0_sel:DWORD
	v_cvt_u32_f32_sdwa v61, v61 dst_sel:BYTE_3 dst_unused:UNUSED_PAD src0_sel:DWORD
	v_cvt_u32_f32_e32 v47, v47
	v_cvt_u32_f32_e32 v46, v46
	v_max_f32_e32 v44, 1.0, v44
	v_max_f32_e32 v45, 1.0, v45
	v_max_f32_e32 v31, 1.0, v31
	v_max_f32_e32 v30, 1.0, v30
	v_fma_f32 v28, v28, s4, 0.5
	v_fma_f32 v29, v29, s4, 0.5
	v_cvt_u32_f32_e32 v27, v27
	v_cvt_u32_f32_e32 v26, v26
	v_max_f32_e32 v24, 1.0, v24
	v_max_f32_e32 v25, 1.0, v25
	global_store_dwordx4 v[120:121], v[128:131], off
	v_or3_b32 v114, v110, v108, v109
	v_lshl_or_b32 v94, v95, 8, v94
	v_add_co_u32_e32 v56, vcc, s77, v120
	v_cvt_u32_f32_sdwa v44, v44 dst_sel:WORD_1 dst_unused:UNUSED_PAD src0_sel:DWORD
	v_cvt_u32_f32_sdwa v45, v45 dst_sel:BYTE_3 dst_unused:UNUSED_PAD src0_sel:DWORD
	v_cvt_u32_f32_e32 v31, v31
	v_cvt_u32_f32_e32 v30, v30
	v_max_f32_e32 v28, 1.0, v28
	v_max_f32_e32 v29, 1.0, v29
	v_cvt_u32_f32_sdwa v24, v24 dst_sel:WORD_1 dst_unused:UNUSED_PAD src0_sel:DWORD
	v_cvt_u32_f32_sdwa v25, v25 dst_sel:BYTE_3 dst_unused:UNUSED_PAD src0_sel:DWORD
	global_store_dwordx4 v[104:105], v[112:115], off
	v_or3_b32 v98, v94, v92, v93
	v_lshl_or_b32 v78, v79, 8, v78
	v_addc_co_u32_e32 v57, vcc, 0, v121, vcc
	s_mov_b32 s2, 0xa000
	v_cvt_u32_f32_sdwa v28, v28 dst_sel:WORD_1 dst_unused:UNUSED_PAD src0_sel:DWORD
	v_cvt_u32_f32_sdwa v29, v29 dst_sel:BYTE_3 dst_unused:UNUSED_PAD src0_sel:DWORD
	global_store_dwordx4 v[88:89], v[96:99], off
	v_or3_b32 v82, v78, v76, v77
	v_lshl_or_b32 v62, v63, 8, v62
	v_add_co_u32_e32 v40, vcc, s2, v120
	global_store_dwordx4 v[72:73], v[80:83], off
	v_or3_b32 v66, v62, v60, v61
	v_lshl_or_b32 v46, v47, 8, v46
	v_addc_co_u32_e32 v41, vcc, 0, v121, vcc
	v_lshl_or_b32 v26, v27, 8, v26
	s_mov_b32 s2, 0xc000
	global_store_dwordx4 v[56:57], v[64:67], off
	v_or3_b32 v50, v46, v44, v45
	v_lshl_or_b32 v30, v31, 8, v30
	v_or3_b32 v35, v26, v24, v25
	v_add_co_u32_e32 v24, vcc, s2, v120
	global_store_dwordx4 v[40:41], v[48:51], off
	v_or3_b32 v34, v30, v28, v29
	v_addc_co_u32_e32 v25, vcc, 0, v121, vcc
	global_store_dwordx4 v[24:25], v[32:35], off
	v_mul_f32_e32 v24, 0x3c800000, v137
	v_pk_mul_f32 v[20:21], v[20:21], v[24:25] op_sel_hi:[1,0]
	s_mov_b32 s33, s35
	v_mul_f32_e32 v21, 0xbfb8aa3b, v21
	v_exp_f32_e32 v21, v21
	v_mul_f32_e32 v20, 0xbfb8aa3b, v20
; __device__ __forceinline__ float sigmoidf_(float v) { return __builtin_amdgcn_rcpf(1.0f + __expf(-v)); }
; #define MEMFENCE asm volatile("" ::: "memory")
; #define G_WAIT_V(n) asm volatile("s_waitcnt vmcnt(" #n ")" ::: "memory")
; #define G_BAR __builtin_amdgcn_s_barrier()
;     template <int KIND> __device__ __forceinline__ void run(f32x4 (&acc)[2][2][4][2], const Unit& u, int tid_in) const {
;     ...
;                 for (int m = 0; m < 4; ++m) { const float r = rs[ai * 4 + m] * (1.0f / GATE_WSCALE); u32x4 w;
; #pragma unroll
;                     for (int bj = 0; bj < 2; ++bj) { f32x4 a = acc[ai][bj][m][0] * r, b = acc[ai][bj][m][1] * r;
; #pragma unroll
;                         for (int j = 0; j < 4; ++j) { a[j] = sigmoidf_(a[j]); b[j] = sigmoidf_(b[j]); }
;                         if (bj == 0) { w.x = pack4_u8c(a); w.y = pack4_u8c(b); } else { w.z = pack4_u8c(a); w.w = pack4_u8c(b); } }
;                     gst[(ai * 4 + m) * 512 + tid] = w; MEMFENCE; }
;     ...
;     G_WAIT_V(0);
;     if (wr == 0) G_BAR;
;     G_BAR;
	v_exp_f32_e32 v25, v20
	s_mov_b32 s36, s34
	v_add_f32_e32 v20, 1.0, v21
	v_rcp_f32_e32 v26, v20
	v_pk_mul_f32 v[20:21], v[22:23], v[24:25] op_sel_hi:[1,0]
	v_add_f32_e32 v22, 1.0, v25
	v_mul_f32_e32 v20, 0xbfb8aa3b, v20
	v_exp_f32_e32 v20, v20
	v_rcp_f32_e32 v22, v22
	v_mul_f32_e32 v21, 0xbfb8aa3b, v21
	v_exp_f32_e32 v21, v21
	v_add_f32_e32 v20, 1.0, v20
	v_fma_f32 v23, v26, s4, 0.5
	v_fma_f32 v22, v22, s4, 0.5
	v_rcp_f32_e32 v20, v20
	v_max_f32_e32 v23, 1.0, v23
	v_max_f32_e32 v22, 1.0, v22
	v_add_f32_e32 v21, 1.0, v21
	v_cvt_u32_f32_e32 v23, v23
	v_cvt_u32_f32_e32 v22, v22
	v_rcp_f32_e32 v21, v21
	v_fma_f32 v20, v20, s4, 0.5
	v_max_f32_e32 v20, 1.0, v20
	v_lshl_or_b32 v22, v23, 8, v22
	v_cvt_u32_f32_sdwa v23, v20 dst_sel:WORD_1 dst_unused:UNUSED_PAD src0_sel:DWORD
	v_fma_f32 v20, v21, s4, 0.5
	v_max_f32_e32 v20, 1.0, v20
	v_cvt_u32_f32_sdwa v25, v20 dst_sel:BYTE_3 dst_unused:UNUSED_PAD src0_sel:DWORD
	s_mov_b64 s[12:13], s[10:11]
	s_mov_b64 s[2:3], s[8:9]
	v_pk_mul_f32 v[20:21], v[16:17], v[24:25] op_sel_hi:[1,0]
	s_nop 0
	v_mul_f32_e32 v16, 0xbfb8aa3b, v21
	v_mul_f32_e32 v20, 0xbfb8aa3b, v20
	v_pk_mul_f32 v[18:19], v[18:19], v[24:25] op_sel_hi:[1,0]
	v_exp_f32_e32 v17, v16
	v_exp_f32_e32 v20, v20
	v_mul_f32_e32 v18, 0xbfb8aa3b, v18
	v_mul_f32_e32 v19, 0xbfb8aa3b, v19
	v_exp_f32_e32 v18, v18
	v_exp_f32_e32 v19, v19
	v_add_f32_e32 v17, 1.0, v17
	v_add_f32_e32 v20, 1.0, v20
	v_rcp_f32_e32 v17, v17
	v_rcp_f32_e32 v20, v20
	v_add_f32_e32 v18, 1.0, v18
	v_add_f32_e32 v19, 1.0, v19
	v_rcp_f32_e32 v18, v18
	v_rcp_f32_e32 v19, v19
	v_fma_f32 v17, v17, s4, 0.5
	v_fma_f32 v20, v20, s4, 0.5
	v_max_f32_e32 v17, 1.0, v17
	v_max_f32_e32 v20, 1.0, v20
	v_fma_f32 v18, v18, s4, 0.5
	v_fma_f32 v19, v19, s4, 0.5
	v_pk_mul_f32 v[12:13], v[12:13], v[24:25] op_sel_hi:[1,0]
	v_cvt_u32_f32_e32 v17, v17
	v_cvt_u32_f32_e32 v20, v20
	v_max_f32_e32 v18, 1.0, v18
	v_max_f32_e32 v19, 1.0, v19
	v_mul_f32_e32 v13, 0xbfb8aa3b, v13
	v_cvt_u32_f32_sdwa v18, v18 dst_sel:WORD_1 dst_unused:UNUSED_PAD src0_sel:DWORD
	v_cvt_u32_f32_sdwa v19, v19 dst_sel:BYTE_3 dst_unused:UNUSED_PAD src0_sel:DWORD
	v_exp_f32_e32 v13, v13
	v_pk_mul_f32 v[8:9], v[8:9], v[24:25] op_sel_hi:[1,0]
	v_lshl_or_b32 v17, v17, 8, v20
	v_mul_f32_e32 v12, 0xbfb8aa3b, v12
	v_mul_f32_e32 v9, 0xbfb8aa3b, v9
	v_or3_b32 v17, v17, v18, v19
	v_exp_f32_e32 v18, v12
	v_add_f32_e32 v12, 1.0, v13
	v_exp_f32_e32 v9, v9
	v_rcp_f32_e32 v19, v12
	v_mul_f32_e32 v8, 0xbfb8aa3b, v8
	v_pk_mul_f32 v[12:13], v[14:15], v[24:25] op_sel_hi:[1,0]
	v_add_f32_e32 v14, 1.0, v18
	v_exp_f32_e32 v18, v8
	v_add_f32_e32 v8, 1.0, v9
	v_fma_f32 v15, v19, s4, 0.5
	v_rcp_f32_e32 v19, v8
	v_pk_mul_f32 v[8:9], v[10:11], v[24:25] op_sel_hi:[1,0]
	v_mul_f32_e32 v12, 0xbfb8aa3b, v12
	v_mul_f32_e32 v8, 0xbfb8aa3b, v8
	v_mul_f32_e32 v9, 0xbfb8aa3b, v9
	v_mul_f32_e32 v13, 0xbfb8aa3b, v13
	v_exp_f32_e32 v8, v8
	v_exp_f32_e32 v9, v9
	v_exp_f32_e32 v12, v12
	v_exp_f32_e32 v13, v13
	v_add_f32_e32 v10, 1.0, v18
	v_rcp_f32_e32 v10, v10
	v_add_f32_e32 v8, 1.0, v8
	v_add_f32_e32 v9, 1.0, v9
	v_rcp_f32_e32 v14, v14
	v_add_f32_e32 v12, 1.0, v12
	v_add_f32_e32 v13, 1.0, v13
	v_rcp_f32_e32 v8, v8
	v_rcp_f32_e32 v9, v9
	v_rcp_f32_e32 v12, v12
	v_rcp_f32_e32 v13, v13
	v_fma_f32 v11, v19, s4, 0.5
	v_fma_f32 v10, v10, s4, 0.5
	v_fma_f32 v14, v14, s4, 0.5
	v_max_f32_e32 v11, 1.0, v11
	v_max_f32_e32 v10, 1.0, v10
	v_fma_f32 v8, v8, s4, 0.5
	v_fma_f32 v9, v9, s4, 0.5
	v_max_f32_e32 v15, 1.0, v15
	v_max_f32_e32 v14, 1.0, v14
	v_fma_f32 v12, v12, s4, 0.5
	v_fma_f32 v13, v13, s4, 0.5
	v_cvt_u32_f32_e32 v11, v11
	v_cvt_u32_f32_e32 v10, v10
	v_max_f32_e32 v8, 1.0, v8
	v_max_f32_e32 v9, 1.0, v9
	v_cvt_u32_f32_e32 v15, v15
	v_cvt_u32_f32_e32 v14, v14
	v_max_f32_e32 v12, 1.0, v12
	v_max_f32_e32 v13, 1.0, v13
	v_cvt_u32_f32_sdwa v8, v8 dst_sel:WORD_1 dst_unused:UNUSED_PAD src0_sel:DWORD
	v_cvt_u32_f32_sdwa v9, v9 dst_sel:BYTE_3 dst_unused:UNUSED_PAD src0_sel:DWORD
	v_cvt_u32_f32_sdwa v12, v12 dst_sel:WORD_1 dst_unused:UNUSED_PAD src0_sel:DWORD
	v_cvt_u32_f32_sdwa v13, v13 dst_sel:BYTE_3 dst_unused:UNUSED_PAD src0_sel:DWORD
	v_lshl_or_b32 v10, v11, 8, v10
	v_lshl_or_b32 v14, v15, 8, v14
	v_or3_b32 v19, v10, v8, v9
	v_add_co_u32_e32 v8, vcc, 0xe000, v120
	v_or3_b32 v16, v22, v23, v25
	v_or3_b32 v18, v14, v12, v13
	v_addc_co_u32_e32 v9, vcc, 0, v121, vcc
	global_store_dwordx4 v[8:9], v[16:19], off
	s_and_b64 vcc, exec, s[6:7]
	s_cbranch_vccz .LBB0_867
	s_waitcnt vmcnt(0)
	s_cmpk_gt_u32 s16, 0xff
	s_cbranch_scc1 .LBB0_876
	s_barrier

; __global__ void __launch_bounds__(512) fwd_megakernel(Params Parg) {
	.amdhsa_kernel _Z14fwd_megakernel6Params
		.amdhsa_group_segment_fixed_size 0
		.amdhsa_private_segment_fixed_size 0
		.amdhsa_kernarg_size 472
		.amdhsa_user_sgpr_count 2
		.amdhsa_user_sgpr_dispatch_ptr 0
		.amdhsa_user_sgpr_queue_ptr 0
		.amdhsa_user_sgpr_kernarg_segment_ptr 1
		.amdhsa_user_sgpr_dispatch_id 0
		.amdhsa_user_sgpr_kernarg_preload_length 0
		.amdhsa_user_sgpr_kernarg_preload_offset 0
		.amdhsa_user_sgpr_private_segment_size 0
		.amdhsa_uses_dynamic_stack 0
		.amdhsa_enable_private_segment 0
		.amdhsa_system_sgpr_workgroup_id_x 1
		.amdhsa_system_sgpr_workgroup_id_y 0
		.amdhsa_system_sgpr_workgroup_id_z 0
		.amdhsa_system_sgpr_workgroup_info 0
		.amdhsa_system_vgpr_workitem_id 2
		.amdhsa_next_free_vgpr 240
		.amdhsa_next_free_sgpr 100
		.amdhsa_accum_offset 240
		.amdhsa_reserve_vcc 1
		.amdhsa_float_round_mode_32 0
		.amdhsa_float_round_mode_16_64 0
		.amdhsa_float_denorm_mode_32 3
		.amdhsa_float_denorm_mode_16_64 3
		.amdhsa_dx10_clamp 1
		.amdhsa_ieee_mode 1
		.amdhsa_fp16_overflow 0
		.amdhsa_tg_split 0
		.amdhsa_exception_fp_ieee_invalid_op 0
		.amdhsa_exception_fp_denorm_src 0
		.amdhsa_exception_fp_ieee_div_zero 0
		.amdhsa_exception_fp_ieee_overflow 0
		.amdhsa_exception_fp_ieee_underflow 0
		.amdhsa_exception_fp_ieee_inexact 0
		.amdhsa_exception_int_div_zero 0
	.end_amdhsa_kernel

; __global__ void __launch_bounds__(512) fwd_megakernel(Params Parg) {
amdhsa.kernels:
  - .agpr_count:     0
    .args:
      - .offset:         0
        .size:           216
        .value_kind:     by_value
      - .offset:         216
        .size:           4
        .value_kind:     hidden_block_count_x
      - .offset:         220
        .size:           4
        .value_kind:     hidden_block_count_y
      - .offset:         224
        .size:           4
        .value_kind:     hidden_block_count_z
      - .offset:         228
        .size:           2
        .value_kind:     hidden_group_size_x
      - .offset:         230
        .size:           2
        .value_kind:     hidden_group_size_y
      - .offset:         232
        .size:           2
        .value_kind:     hidden_group_size_z
      - .offset:         234
        .size:           2
        .value_kind:     hidden_remainder_x
      - .offset:         236
        .size:           2
        .value_kind:     hidden_remainder_y
      - .offset:         238
        .size:           2
        .value_kind:     hidden_remainder_z
      - .offset:         256
        .size:           8
        .value_kind:     hidden_global_offset_x
      - .offset:         264
        .size:           8
        .value_kind:     hidden_global_offset_y
      - .offset:         272
        .size:           8
        .value_kind:     hidden_global_offset_z
      - .offset:         280
        .size:           2
        .value_kind:     hidden_grid_dims
      - .offset:         304
        .size:           8
        .value_kind:     hidden_multigrid_sync_arg
      - .offset:         336
        .size:           4
        .value_kind:     hidden_dynamic_lds_size
    .group_segment_fixed_size: 0
    .kernarg_segment_align: 8
    .kernarg_segment_size: 472
    .language:       OpenCL C
    .language_version:
      - 2
      - 0
    .max_flat_workgroup_size: 512
    .name:           _Z14fwd_megakernel6Params
    .private_segment_fixed_size: 0
    .sgpr_count:     106
    .sgpr_spill_count: 328
    .symbol:         _Z14fwd_megakernel6Params.kd
    .uniform_work_group_size: 1
    .uses_dynamic_stack: false
    .vgpr_count:     240
    .vgpr_spill_count: 0
    .wavefront_size: 64
